# GEMM K-loops: loop increments hoisted before the last MFMA burst's barrier; LDS wait of the two 4-read phases moved in front of their barrier
# speedup vs baseline: 1.0215x; 1.0013x over previous
; #define PG8_STAGE(bufoff, gbase, v0, v1) do { \
;         __builtin_amdgcn_global_load_lds((const unsigned*)((const char*)(gbase) + (v0)), (LAS unsigned*)(lds + (bufoff) + ldsw), 16, 0, 0); \
;         __builtin_amdgcn_global_load_lds((const unsigned*)((const char*)(gbase) + (v1)), (LAS unsigned*)(lds + (bufoff) + ldsw + 8192), 16, 0, 0); } while (0)
; #define PG8_LDA(dst, b, h) do { _Pragma("unroll") for (int m = 0; m < 4; ++m) _Pragma("unroll") for (int k = 0; k < 2; ++k) dst[m][k] = *(const LAS bf16x8*)(lds + PG8_SA(b, h) + aoff + m * 2048 + k * 1024); } while (0)
; #define PG8_LDB(dst, b, h) do { _Pragma("unroll") for (int n = 0; n < 2; ++n) _Pragma("unroll") for (int k = 0; k < 2; ++k) dst[n][k] = *(const LAS bf16x8*)(lds + PG8_SB(b, h) + boff + n * 2048 + k * 1024); } while (0)
; #define PG8_MMA(ai, bj, At, Bt) do { __builtin_amdgcn_s_setprio(1); _Pragma("unroll") for (int m = 0; m < 4; ++m) _Pragma("unroll") for (int n = 0; n < 2; ++n) _Pragma("unroll") for (int k = 0; k < 2; ++k) \
;         acc[ai][bj][m][n] = __builtin_amdgcn_mfma_f32_16x16x32_bf16(Bt[n][k], At[m][k], acc[ai][bj][m][n], 0, 0, 0); __builtin_amdgcn_s_setprio(0); } while (0)
; #define PG8_WAIT_V(n) asm volatile("s_waitcnt vmcnt(" #n ")" ::: "memory")
; #define PG8_WAIT_L(n) asm volatile("s_waitcnt lgkmcnt(" #n ")" ::: "memory")
; #define PG8_BAR __builtin_amdgcn_s_barrier()
; #define PG8_SCHED __builtin_amdgcn_sched_barrier(0)
; template <class Epi, class Sched>
; __device__ __forceinline__ void gemm_phase(LAS unsigned char* lds, const Sched& S, const Epi& E) {
;     ...
;             PG8_LDB(B0, 0, 0); PG8_SCHED; PG8_LDA(At, 0, 0); PG8_STAGE(PG8_SA(1, 1), a1 + hA, vA0, vA1);
;             PG8_WAIT_L(8); PG8_BAR; PG8_WAIT_L(0); PG8_MMA(0, 0, At, B0); PG8_BAR; PG8_SCHED;
;             PG8_LDB(B1, 0, 1); PG8_STAGE(PG8_SB(0, 0), b2, xB0, xB1);
;             PG8_BAR; PG8_WAIT_L(0); PG8_MMA(0, 1, At, B1); PG8_BAR;
;             PG8_LDA(At, 0, 1); PG8_STAGE(PG8_SA(0, 0), a2, xA0, xA1);
;             PG8_BAR; PG8_WAIT_L(0); PG8_MMA(1, 0, At, B0); PG8_BAR; PG8_SCHED;
;             PG8_STAGE(PG8_SB(0, 1), b2 + xhB, xB0, xB1);
;             PG8_WAIT_V(6); PG8_BAR; PG8_MMA(1, 1, At, B1); PG8_BAR;
;             PG8_LDB(B0, 1, 0); PG8_SCHED; PG8_LDA(At, 1, 0); PG8_STAGE(PG8_SA(0, 1), a2 + xhA, xA0, xA1);
.Lrot_body_0:
	ds_read_b128 v[158:161], v138
	ds_read_b128 v[182:185], v138 offset:1024
	ds_read_b128 v[186:189], v138 offset:2048
	ds_read_b128 v[190:193], v138 offset:3072
	v_lshl_add_u64 v[226:227], s[26:27], 0, v[132:133]
	s_add_i32 m0, s48, 0xc000
	ds_read_b128 v[194:197], v154
	ds_read_b128 v[198:201], v154 offset:1024
	ds_read_b128 v[202:205], v154 offset:2048
	ds_read_b128 v[206:209], v154 offset:3072
	ds_read_b128 v[210:213], v154 offset:4096
	ds_read_b128 v[214:217], v154 offset:5120
	ds_read_b128 v[218:221], v154 offset:6144
	ds_read_b128 v[222:225], v154 offset:7168
	global_load_lds_dwordx4 v[226:227], off
	v_lshl_add_u64 v[226:227], s[26:27], 0, v[134:135]
	s_add_i32 m0, s48, 0xe000
	s_nop 0
	global_load_lds_dwordx4 v[226:227], off
	s_waitcnt lgkmcnt(8)
	s_barrier
	s_waitcnt lgkmcnt(0)
	v_mfma_f32_16x16x32_bf16 v[124:127], v[158:161], v[194:197], v[124:127]
	v_mfma_f32_16x16x32_bf16 v[120:123], v[186:189], v[194:197], v[120:123]
	v_mfma_f32_16x16x32_bf16 v[116:119], v[158:161], v[202:205], v[116:119]
	v_mfma_f32_16x16x32_bf16 v[112:115], v[186:189], v[202:205], v[112:115]
	v_mfma_f32_16x16x32_bf16 v[100:103], v[158:161], v[210:213], v[100:103]
	v_mfma_f32_16x16x32_bf16 v[96:99], v[186:189], v[210:213], v[96:99]
	v_mfma_f32_16x16x32_bf16 v[84:87], v[158:161], v[218:221], v[84:87]
	v_mfma_f32_16x16x32_bf16 v[80:83], v[186:189], v[218:221], v[80:83]
	v_mfma_f32_16x16x32_bf16 v[124:127], v[182:185], v[198:201], v[124:127]
	v_mfma_f32_16x16x32_bf16 v[120:123], v[190:193], v[198:201], v[120:123]
	v_mfma_f32_16x16x32_bf16 v[116:119], v[182:185], v[206:209], v[116:119]
	v_mfma_f32_16x16x32_bf16 v[112:115], v[190:193], v[206:209], v[112:115]
	v_mfma_f32_16x16x32_bf16 v[100:103], v[182:185], v[214:217], v[100:103]
	v_mfma_f32_16x16x32_bf16 v[96:99], v[190:193], v[214:217], v[96:99]
	v_mfma_f32_16x16x32_bf16 v[84:87], v[182:185], v[222:225], v[84:87]
	v_mfma_f32_16x16x32_bf16 v[80:83], v[190:193], v[222:225], v[80:83]
	s_barrier
	s_add_i32 s69, 0, 0x14000
	s_add_i32 s21, s21, s43
	v_add_u32_e32 v138, s69, v153
	s_mov_b32 m0, s21
	ds_read_b128 v[226:229], v138
	ds_read_b128 v[230:233], v138 offset:1024
	ds_read_b128 v[234:237], v138 offset:2048
	ds_read_b128 v[238:241], v138 offset:3072
	global_load_lds_dwordx4 v136, s[38:39]
	s_add_i32 m0, s21, 0x2000
	v_mov_b32_e32 v147, v137
	global_load_lds_dwordx4 v146, s[38:39]
	v_lshl_add_u64 v[242:243], s[38:39], 0, v[136:137]
	v_lshl_add_u64 v[244:245], s[38:39], 0, v[146:147]
	s_mov_b32 m0, s48
	v_lshl_add_u64 v[246:247], s[40:41], 0, v[150:151]
	s_waitcnt lgkmcnt(0)
	s_barrier
	v_mfma_f32_16x16x32_bf16 v[108:111], v[226:229], v[194:197], v[108:111]
	v_mfma_f32_16x16x32_bf16 v[104:107], v[234:237], v[194:197], v[104:107]
	v_mfma_f32_16x16x32_bf16 v[92:95], v[226:229], v[202:205], v[92:95]
	v_mfma_f32_16x16x32_bf16 v[88:91], v[234:237], v[202:205], v[88:91]
	v_mfma_f32_16x16x32_bf16 v[76:79], v[226:229], v[210:213], v[76:79]
	v_mfma_f32_16x16x32_bf16 v[72:75], v[234:237], v[210:213], v[72:75]
	v_mfma_f32_16x16x32_bf16 v[68:71], v[226:229], v[218:221], v[68:71]
	v_mfma_f32_16x16x32_bf16 v[64:67], v[234:237], v[218:221], v[64:67]
	v_mfma_f32_16x16x32_bf16 v[108:111], v[230:233], v[198:201], v[108:111]
	v_mfma_f32_16x16x32_bf16 v[104:107], v[238:241], v[198:201], v[104:107]
	v_mfma_f32_16x16x32_bf16 v[92:95], v[230:233], v[206:209], v[92:95]
	v_mfma_f32_16x16x32_bf16 v[88:91], v[238:241], v[206:209], v[88:91]
	v_mfma_f32_16x16x32_bf16 v[76:79], v[230:233], v[214:217], v[76:79]
	v_mfma_f32_16x16x32_bf16 v[72:75], v[238:241], v[214:217], v[72:75]
	v_mfma_f32_16x16x32_bf16 v[68:71], v[230:233], v[222:225], v[68:71]
	v_mfma_f32_16x16x32_bf16 v[64:67], v[238:241], v[222:225], v[64:67]
	s_barrier
	ds_read_b128 v[194:197], v154 offset:16384
	ds_read_b128 v[198:201], v154 offset:17408
	ds_read_b128 v[202:205], v154 offset:18432
	ds_read_b128 v[206:209], v154 offset:19456
	ds_read_b128 v[210:213], v154 offset:20480
	ds_read_b128 v[214:217], v154 offset:21504
	ds_read_b128 v[218:221], v154 offset:22528
	ds_read_b128 v[222:225], v154 offset:23552
	global_load_lds_dwordx4 v[246:247], off
	v_lshl_add_u64 v[248:249], s[40:41], 0, v[148:149]
	s_mov_b32 m0, s49
	s_nop 0
	global_load_lds_dwordx4 v[248:249], off
	s_barrier
	s_waitcnt lgkmcnt(0)
	v_mfma_f32_16x16x32_bf16 v[60:63], v[158:161], v[194:197], v[60:63]
	v_mfma_f32_16x16x32_bf16 v[56:59], v[186:189], v[194:197], v[56:59]
	v_mfma_f32_16x16x32_bf16 v[52:55], v[158:161], v[202:205], v[52:55]
	v_mfma_f32_16x16x32_bf16 v[44:47], v[186:189], v[202:205], v[44:47]
	v_mfma_f32_16x16x32_bf16 v[36:39], v[158:161], v[210:213], v[36:39]
	v_mfma_f32_16x16x32_bf16 v[28:31], v[186:189], v[210:213], v[28:31]
	v_mfma_f32_16x16x32_bf16 v[20:23], v[158:161], v[218:221], v[20:23]
	v_mfma_f32_16x16x32_bf16 v[12:15], v[186:189], v[218:221], v[12:15]
	v_mfma_f32_16x16x32_bf16 v[60:63], v[182:185], v[198:201], v[60:63]
	v_mfma_f32_16x16x32_bf16 v[56:59], v[190:193], v[198:201], v[56:59]
	v_mfma_f32_16x16x32_bf16 v[52:55], v[182:185], v[206:209], v[52:55]
	v_mfma_f32_16x16x32_bf16 v[44:47], v[190:193], v[206:209], v[44:47]
	v_mfma_f32_16x16x32_bf16 v[36:39], v[182:185], v[214:217], v[36:39]
	v_mfma_f32_16x16x32_bf16 v[28:31], v[190:193], v[214:217], v[28:31]
	v_mfma_f32_16x16x32_bf16 v[20:23], v[182:185], v[222:225], v[20:23]
	v_mfma_f32_16x16x32_bf16 v[12:15], v[190:193], v[222:225], v[12:15]
	s_barrier
	s_add_u32 s70, s38, 0x80000
	s_addc_u32 s71, s39, 0
	s_add_i32 s21, s69, s43
	s_mov_b32 m0, s21
	s_nop 0
	global_load_lds_dwordx4 v136, s[70:71]
	s_add_i32 m0, s21, 0x2000
	s_nop 0
	global_load_lds_dwordx4 v146, s[70:71]
	s_add_i32 s21, 0, 0x18000
	v_add_u32_e32 v138, s21, v153
	s_waitcnt vmcnt(6)
	s_barrier
; #define PG8_STAGE(bufoff, gbase, v0, v1) do { \
;         __builtin_amdgcn_global_load_lds((const unsigned*)((const char*)(gbase) + (v0)), (LAS unsigned*)(lds + (bufoff) + ldsw), 16, 0, 0); \
;         __builtin_amdgcn_global_load_lds((const unsigned*)((const char*)(gbase) + (v1)), (LAS unsigned*)(lds + (bufoff) + ldsw + 8192), 16, 0, 0); } while (0)
; #define PG8_LDA(dst, b, h) do { _Pragma("unroll") for (int m = 0; m < 4; ++m) _Pragma("unroll") for (int k = 0; k < 2; ++k) dst[m][k] = *(const LAS bf16x8*)(lds + PG8_SA(b, h) + aoff + m * 2048 + k * 1024); } while (0)
; #define PG8_LDB(dst, b, h) do { _Pragma("unroll") for (int n = 0; n < 2; ++n) _Pragma("unroll") for (int k = 0; k < 2; ++k) dst[n][k] = *(const LAS bf16x8*)(lds + PG8_SB(b, h) + boff + n * 2048 + k * 1024); } while (0)
; #define PG8_MMA(ai, bj, At, Bt) do { __builtin_amdgcn_s_setprio(1); _Pragma("unroll") for (int m = 0; m < 4; ++m) _Pragma("unroll") for (int n = 0; n < 2; ++n) _Pragma("unroll") for (int k = 0; k < 2; ++k) \
;         acc[ai][bj][m][n] = __builtin_amdgcn_mfma_f32_16x16x32_bf16(Bt[n][k], At[m][k], acc[ai][bj][m][n], 0, 0, 0); __builtin_amdgcn_s_setprio(0); } while (0)
; #define PG8_WAIT_V(n) asm volatile("s_waitcnt vmcnt(" #n ")" ::: "memory")
; #define PG8_WAIT_L(n) asm volatile("s_waitcnt lgkmcnt(" #n ")" ::: "memory")
; #define PG8_BAR __builtin_amdgcn_s_barrier()
; #define PG8_SCHED __builtin_amdgcn_sched_barrier(0)
; template <class Epi, class Sched>
; __device__ __forceinline__ void gemm_phase(LAS unsigned char* lds, const Sched& S, const Epi& E) {
;     ...
;             PG8_WAIT_V(6); PG8_BAR; PG8_MMA(1, 1, At, B1); PG8_BAR;
;             PG8_LDB(B0, 1, 0); PG8_SCHED; PG8_LDA(At, 1, 0); PG8_STAGE(PG8_SA(0, 1), a2 + xhA, xA0, xA1);
;             PG8_WAIT_L(8); PG8_BAR; PG8_WAIT_L(0); PG8_MMA(0, 0, At, B0); PG8_BAR; PG8_SCHED;
;             PG8_LDB(B1, 1, 1); PG8_STAGE(PG8_SB(1, 0), b3, xB0, xB1);
;             PG8_BAR; PG8_WAIT_L(0); PG8_MMA(0, 1, At, B1); PG8_BAR;
	v_mfma_f32_16x16x32_bf16 v[48:51], v[226:229], v[194:197], v[48:51]
	v_mfma_f32_16x16x32_bf16 v[40:43], v[234:237], v[194:197], v[40:43]
	v_mfma_f32_16x16x32_bf16 v[32:35], v[226:229], v[202:205], v[32:35]
	v_mfma_f32_16x16x32_bf16 v[24:27], v[234:237], v[202:205], v[24:27]
	v_mfma_f32_16x16x32_bf16 v[16:19], v[226:229], v[210:213], v[16:19]
	v_mfma_f32_16x16x32_bf16 v[8:11], v[234:237], v[210:213], v[8:11]
	v_mfma_f32_16x16x32_bf16 v[4:7], v[226:229], v[218:221], v[4:7]
	v_mfma_f32_16x16x32_bf16 v[0:3], v[234:237], v[218:221], v[0:3]
	v_mfma_f32_16x16x32_bf16 v[48:51], v[230:233], v[198:201], v[48:51]
	v_mfma_f32_16x16x32_bf16 v[40:43], v[238:241], v[198:201], v[40:43]
	v_mfma_f32_16x16x32_bf16 v[32:35], v[230:233], v[206:209], v[32:35]
	v_mfma_f32_16x16x32_bf16 v[24:27], v[238:241], v[206:209], v[24:27]
	v_mfma_f32_16x16x32_bf16 v[16:19], v[230:233], v[214:217], v[16:19]
	v_mfma_f32_16x16x32_bf16 v[8:11], v[238:241], v[214:217], v[8:11]
	v_mfma_f32_16x16x32_bf16 v[4:7], v[230:233], v[222:225], v[4:7]
	v_mfma_f32_16x16x32_bf16 v[0:3], v[238:241], v[222:225], v[0:3]
	s_barrier
	ds_read_b128 v[158:161], v138
	ds_read_b128 v[182:185], v138 offset:1024
	ds_read_b128 v[186:189], v138 offset:2048
	ds_read_b128 v[190:193], v138 offset:3072
	s_add_u32 s40, s40, 0x80000
	s_addc_u32 s41, s41, 0
	s_mov_b32 m0, s50
	v_lshl_add_u64 v[150:151], s[40:41], 0, v[150:151]
	ds_read_b128 v[194:197], v154 offset:32768
	ds_read_b128 v[198:201], v154 offset:33792
	ds_read_b128 v[202:205], v154 offset:34816
	ds_read_b128 v[206:209], v154 offset:35840
	ds_read_b128 v[210:213], v154 offset:36864
	ds_read_b128 v[214:217], v154 offset:37888
	ds_read_b128 v[218:221], v154 offset:38912
	ds_read_b128 v[222:225], v154 offset:39936
	global_load_lds_dwordx4 v[150:151], off
	v_lshl_add_u64 v[148:149], s[40:41], 0, v[148:149]
	s_mov_b32 m0, s51
	s_nop 0
	global_load_lds_dwordx4 v[148:149], off
	s_waitcnt lgkmcnt(8)
	s_barrier
	s_waitcnt lgkmcnt(0)
	v_mfma_f32_16x16x32_bf16 v[124:127], v[158:161], v[194:197], v[124:127]
	v_mfma_f32_16x16x32_bf16 v[120:123], v[186:189], v[194:197], v[120:123]
	v_mfma_f32_16x16x32_bf16 v[116:119], v[158:161], v[202:205], v[116:119]
	v_mfma_f32_16x16x32_bf16 v[112:115], v[186:189], v[202:205], v[112:115]
	v_mfma_f32_16x16x32_bf16 v[100:103], v[158:161], v[210:213], v[100:103]
	v_mfma_f32_16x16x32_bf16 v[96:99], v[186:189], v[210:213], v[96:99]
	v_mfma_f32_16x16x32_bf16 v[84:87], v[158:161], v[218:221], v[84:87]
	v_mfma_f32_16x16x32_bf16 v[80:83], v[186:189], v[218:221], v[80:83]
	v_mfma_f32_16x16x32_bf16 v[124:127], v[182:185], v[198:201], v[124:127]
	v_mfma_f32_16x16x32_bf16 v[120:123], v[190:193], v[198:201], v[120:123]
	v_mfma_f32_16x16x32_bf16 v[116:119], v[182:185], v[206:209], v[116:119]
	v_mfma_f32_16x16x32_bf16 v[112:115], v[190:193], v[206:209], v[112:115]
	v_mfma_f32_16x16x32_bf16 v[100:103], v[182:185], v[214:217], v[100:103]
	v_mfma_f32_16x16x32_bf16 v[96:99], v[190:193], v[214:217], v[96:99]
	v_mfma_f32_16x16x32_bf16 v[84:87], v[182:185], v[222:225], v[84:87]
	v_mfma_f32_16x16x32_bf16 v[80:83], v[190:193], v[222:225], v[80:83]
	s_barrier
	s_add_i32 s40, 0, 0x1c000
	s_add_i32 s21, s21, s43
	v_add_u32_e32 v138, s40, v153
	v_lshl_add_u64 v[238:239], v[242:243], 0, s[44:45]
	s_mov_b32 m0, s21
	ds_read_b128 v[148:151], v138
	ds_read_b128 v[226:229], v138 offset:1024
	ds_read_b128 v[230:233], v138 offset:2048
	ds_read_b128 v[234:237], v138 offset:3072
	global_load_lds_dwordx4 v[238:239], off
	v_lshl_add_u64 v[238:239], v[244:245], 0, s[44:45]
	s_add_i32 m0, s21, 0x2000
	s_nop 0
	global_load_lds_dwordx4 v[238:239], off
	s_mov_b32 m0, s64
	v_lshl_add_u64 v[238:239], v[246:247], 0, s[44:45]
	s_waitcnt lgkmcnt(0)
	s_barrier
; #define PG8_STAGE(bufoff, gbase, v0, v1) do { \
;         __builtin_amdgcn_global_load_lds((const unsigned*)((const char*)(gbase) + (v0)), (LAS unsigned*)(lds + (bufoff) + ldsw), 16, 0, 0); \
;         __builtin_amdgcn_global_load_lds((const unsigned*)((const char*)(gbase) + (v1)), (LAS unsigned*)(lds + (bufoff) + ldsw + 8192), 16, 0, 0); } while (0)
; #define PG8_LDA(dst, b, h) do { _Pragma("unroll") for (int m = 0; m < 4; ++m) _Pragma("unroll") for (int k = 0; k < 2; ++k) dst[m][k] = *(const LAS bf16x8*)(lds + PG8_SA(b, h) + aoff + m * 2048 + k * 1024); } while (0)
; #define PG8_MMA(ai, bj, At, Bt) do { __builtin_amdgcn_s_setprio(1); _Pragma("unroll") for (int m = 0; m < 4; ++m) _Pragma("unroll") for (int n = 0; n < 2; ++n) _Pragma("unroll") for (int k = 0; k < 2; ++k) \
;         acc[ai][bj][m][n] = __builtin_amdgcn_mfma_f32_16x16x32_bf16(Bt[n][k], At[m][k], acc[ai][bj][m][n], 0, 0, 0); __builtin_amdgcn_s_setprio(0); } while (0)
; #define PG8_WAIT_V(n) asm volatile("s_waitcnt vmcnt(" #n ")" ::: "memory")
; #define PG8_WAIT_L(n) asm volatile("s_waitcnt lgkmcnt(" #n ")" ::: "memory")
; #define PG8_BAR __builtin_amdgcn_s_barrier()
; #define PG8_SCHED __builtin_amdgcn_sched_barrier(0)
; template <class Epi, class Sched>
; __device__ __forceinline__ void gemm_phase(LAS unsigned char* lds, const Sched& S, const Epi& E) {
;     ...
;         for (int t = 0; t < nt; t += 2) {
;             const bool last = (t == nt - 2);
;             const char* a1 = cA + (size_t)(t + 1) * kstep;
;             const char* a2 = last ? nA : cA + (size_t)(t + 2) * kstep; const char* b2 = last ? nB : cB + (size_t)(t + 2) * kstep;
;             const char* a3 = a2 + kstep; const char* b3 = b2 + kstep;
;             const unsigned xA0 = last ? nvA0 : vA0, xA1 = last ? nvA1 : vA1, xB0 = last ? nvB0 : vB0, xB1 = last ? nvB1 : vB1;
;     ...
;             PG8_BAR; PG8_WAIT_L(0); PG8_MMA(0, 1, At, B1); PG8_BAR;
;             PG8_LDA(At, 1, 1); PG8_STAGE(PG8_SA(1, 0), a3, xA0, xA1);
;             PG8_BAR; PG8_WAIT_L(0); PG8_MMA(1, 0, At, B0); PG8_BAR; PG8_SCHED;
;             PG8_STAGE(PG8_SB(1, 1), b3 + xhB, xB0, xB1);
;             PG8_WAIT_V(6); PG8_BAR; PG8_MMA(1, 1, At, B1); PG8_BAR;
	v_mfma_f32_16x16x32_bf16 v[108:111], v[148:151], v[194:197], v[108:111]
	v_mfma_f32_16x16x32_bf16 v[104:107], v[230:233], v[194:197], v[104:107]
	v_mfma_f32_16x16x32_bf16 v[92:95], v[148:151], v[202:205], v[92:95]
	v_mfma_f32_16x16x32_bf16 v[88:91], v[230:233], v[202:205], v[88:91]
	v_mfma_f32_16x16x32_bf16 v[76:79], v[148:151], v[210:213], v[76:79]
	v_mfma_f32_16x16x32_bf16 v[72:75], v[230:233], v[210:213], v[72:75]
	v_mfma_f32_16x16x32_bf16 v[68:71], v[148:151], v[218:221], v[68:71]
	v_mfma_f32_16x16x32_bf16 v[64:67], v[230:233], v[218:221], v[64:67]
	v_mfma_f32_16x16x32_bf16 v[108:111], v[226:229], v[198:201], v[108:111]
	v_mfma_f32_16x16x32_bf16 v[104:107], v[234:237], v[198:201], v[104:107]
	v_mfma_f32_16x16x32_bf16 v[92:95], v[226:229], v[206:209], v[92:95]
	v_mfma_f32_16x16x32_bf16 v[88:91], v[234:237], v[206:209], v[88:91]
	v_mfma_f32_16x16x32_bf16 v[76:79], v[226:229], v[214:217], v[76:79]
	v_mfma_f32_16x16x32_bf16 v[72:75], v[234:237], v[214:217], v[72:75]
	v_mfma_f32_16x16x32_bf16 v[68:71], v[226:229], v[222:225], v[68:71]
	v_mfma_f32_16x16x32_bf16 v[64:67], v[234:237], v[222:225], v[64:67]
	s_barrier
	ds_read_b128 v[194:197], v154 offset:49152
	ds_read_b128 v[198:201], v154 offset:50176
	ds_read_b128 v[202:205], v154 offset:51200
	ds_read_b128 v[206:209], v154 offset:52224
	ds_read_b128 v[210:213], v154 offset:53248
	ds_read_b128 v[214:217], v154 offset:54272
	ds_read_b128 v[218:221], v154 offset:55296
	ds_read_b128 v[222:225], v154 offset:56320
	global_load_lds_dwordx4 v[238:239], off
	v_lshl_add_u64 v[238:239], v[248:249], 0, s[44:45]
	s_mov_b32 m0, s65
	s_nop 0
	global_load_lds_dwordx4 v[238:239], off
	s_barrier
	s_waitcnt lgkmcnt(0)
	v_mfma_f32_16x16x32_bf16 v[60:63], v[158:161], v[194:197], v[60:63]
	v_mfma_f32_16x16x32_bf16 v[56:59], v[186:189], v[194:197], v[56:59]
	v_mfma_f32_16x16x32_bf16 v[52:55], v[158:161], v[202:205], v[52:55]
	v_mfma_f32_16x16x32_bf16 v[44:47], v[186:189], v[202:205], v[44:47]
	v_mfma_f32_16x16x32_bf16 v[36:39], v[158:161], v[210:213], v[36:39]
	v_mfma_f32_16x16x32_bf16 v[28:31], v[186:189], v[210:213], v[28:31]
	v_mfma_f32_16x16x32_bf16 v[20:23], v[158:161], v[218:221], v[20:23]
	v_mfma_f32_16x16x32_bf16 v[12:15], v[186:189], v[218:221], v[12:15]
	v_mfma_f32_16x16x32_bf16 v[60:63], v[182:185], v[198:201], v[60:63]
	v_mfma_f32_16x16x32_bf16 v[56:59], v[190:193], v[198:201], v[56:59]
	v_mfma_f32_16x16x32_bf16 v[52:55], v[182:185], v[206:209], v[52:55]
	v_mfma_f32_16x16x32_bf16 v[44:47], v[190:193], v[206:209], v[44:47]
	v_mfma_f32_16x16x32_bf16 v[36:39], v[182:185], v[214:217], v[36:39]
	v_mfma_f32_16x16x32_bf16 v[28:31], v[190:193], v[214:217], v[28:31]
	v_mfma_f32_16x16x32_bf16 v[20:23], v[182:185], v[222:225], v[20:23]
	v_mfma_f32_16x16x32_bf16 v[12:15], v[190:193], v[222:225], v[12:15]
	s_barrier
	s_add_u32 s38, s38, 0x80080
	s_addc_u32 s39, s39, 0
	s_add_i32 s21, s40, s43
	s_mov_b32 m0, s21
	s_nop 0
	global_load_lds_dwordx4 v136, s[38:39]
	s_add_i32 m0, s21, 0x2000
	s_nop 0
	global_load_lds_dwordx4 v146, s[38:39]
	s_add_i32 s15, s15, 2
	s_add_u32 s26, s26, 0x100
	s_addc_u32 s27, s27, 0
	s_add_u32 s34, s34, 0x100
	s_addc_u32 s35, s35, 0
	s_waitcnt vmcnt(6)
	s_barrier
	v_mfma_f32_16x16x32_bf16 v[48:51], v[148:151], v[194:197], v[48:51]
	v_mfma_f32_16x16x32_bf16 v[40:43], v[230:233], v[194:197], v[40:43]
	v_mfma_f32_16x16x32_bf16 v[32:35], v[148:151], v[202:205], v[32:35]
	v_mfma_f32_16x16x32_bf16 v[24:27], v[230:233], v[202:205], v[24:27]
	v_mfma_f32_16x16x32_bf16 v[16:19], v[148:151], v[210:213], v[16:19]
	v_mfma_f32_16x16x32_bf16 v[8:11], v[230:233], v[210:213], v[8:11]
	v_mfma_f32_16x16x32_bf16 v[4:7], v[148:151], v[218:221], v[4:7]
	v_mfma_f32_16x16x32_bf16 v[0:3], v[230:233], v[218:221], v[0:3]
	v_mfma_f32_16x16x32_bf16 v[48:51], v[226:229], v[198:201], v[48:51]
	v_mfma_f32_16x16x32_bf16 v[40:43], v[234:237], v[198:201], v[40:43]
	v_mfma_f32_16x16x32_bf16 v[32:35], v[226:229], v[206:209], v[32:35]
	v_mfma_f32_16x16x32_bf16 v[24:27], v[234:237], v[206:209], v[24:27]
	v_mfma_f32_16x16x32_bf16 v[16:19], v[226:229], v[214:217], v[16:19]
	v_mfma_f32_16x16x32_bf16 v[8:11], v[234:237], v[214:217], v[8:11]
	v_mfma_f32_16x16x32_bf16 v[4:7], v[226:229], v[222:225], v[4:7]
	v_mfma_f32_16x16x32_bf16 v[0:3], v[234:237], v[222:225], v[0:3]
	s_cmp_gt_u32 s15, 29
	s_cbranch_scc1 .Lrot_exit_0
	s_cmp_eq_u32 s15, 28
	s_cselect_b64 s[40:41], -1, 0
	s_and_b64 vcc, exec, s[40:41]
	v_mov_b64_e32 v[148:149], v[130:131]
	v_mov_b64_e32 v[150:151], v[128:129]
	v_mov_b32_e32 v146, v156
	v_mov_b32_e32 v136, v155
	s_mov_b64 s[38:39], s[24:25]
	s_cbranch_vccnz .Lrot_join_0
	v_mov_b64_e32 v[148:149], v[134:135]
	v_mov_b64_e32 v[150:151], v[132:133]
	v_mov_b32_e32 v146, v142
	v_mov_b32_e32 v136, v144
	s_mov_b64 s[38:39], s[34:35]

; #define PG8_STAGE(bufoff, gbase, v0, v1) do { \
;         __builtin_amdgcn_global_load_lds((const unsigned*)((const char*)(gbase) + (v0)), (LAS unsigned*)(lds + (bufoff) + ldsw), 16, 0, 0); \
;         __builtin_amdgcn_global_load_lds((const unsigned*)((const char*)(gbase) + (v1)), (LAS unsigned*)(lds + (bufoff) + ldsw + 8192), 16, 0, 0); } while (0)
; #define PG8_LDA(dst, b, h) do { _Pragma("unroll") for (int m = 0; m < 4; ++m) _Pragma("unroll") for (int k = 0; k < 2; ++k) dst[m][k] = *(const LAS bf16x8*)(lds + PG8_SA(b, h) + aoff + m * 2048 + k * 1024); } while (0)
; #define PG8_LDB(dst, b, h) do { _Pragma("unroll") for (int n = 0; n < 2; ++n) _Pragma("unroll") for (int k = 0; k < 2; ++k) dst[n][k] = *(const LAS bf16x8*)(lds + PG8_SB(b, h) + boff + n * 2048 + k * 1024); } while (0)
; #define PG8_MMA(ai, bj, At, Bt) do { __builtin_amdgcn_s_setprio(1); _Pragma("unroll") for (int m = 0; m < 4; ++m) _Pragma("unroll") for (int n = 0; n < 2; ++n) _Pragma("unroll") for (int k = 0; k < 2; ++k) \
;         acc[ai][bj][m][n] = __builtin_amdgcn_mfma_f32_16x16x32_bf16(Bt[n][k], At[m][k], acc[ai][bj][m][n], 0, 0, 0); __builtin_amdgcn_s_setprio(0); } while (0)
; #define PG8_WAIT_V(n) asm volatile("s_waitcnt vmcnt(" #n ")" ::: "memory")
; #define PG8_WAIT_L(n) asm volatile("s_waitcnt lgkmcnt(" #n ")" ::: "memory")
; #define PG8_BAR __builtin_amdgcn_s_barrier()
; #define PG8_SCHED __builtin_amdgcn_sched_barrier(0)
; template <class Epi, class Sched>
; __device__ __forceinline__ void gemm_phase(LAS unsigned char* lds, const Sched& S, const Epi& E) {
;     ...
;             PG8_LDB(B0, 0, 0); PG8_SCHED; PG8_LDA(At, 0, 0); PG8_STAGE(PG8_SA(1, 1), a1 + hA, vA0, vA1);
;             PG8_WAIT_L(8); PG8_BAR; PG8_WAIT_L(0); PG8_MMA(0, 0, At, B0); PG8_BAR; PG8_SCHED;
;             PG8_LDB(B1, 0, 1); PG8_STAGE(PG8_SB(0, 0), b2, xB0, xB1);
;             PG8_BAR; PG8_WAIT_L(0); PG8_MMA(0, 1, At, B1); PG8_BAR;
;             PG8_LDA(At, 0, 1); PG8_STAGE(PG8_SA(0, 0), a2, xA0, xA1);
;             PG8_BAR; PG8_WAIT_L(0); PG8_MMA(1, 0, At, B0); PG8_BAR; PG8_SCHED;
;             PG8_STAGE(PG8_SB(0, 1), b2 + xhB, xB0, xB1);
;             PG8_WAIT_V(6); PG8_BAR; PG8_MMA(1, 1, At, B1); PG8_BAR;
;             PG8_LDB(B0, 1, 0); PG8_SCHED; PG8_LDA(At, 1, 0); PG8_STAGE(PG8_SA(0, 1), a2 + xhA, xA0, xA1);
.Lrot_body_1:
	ds_read_b128 v[158:161], v138
	ds_read_b128 v[186:189], v138 offset:1024
	ds_read_b128 v[190:193], v138 offset:2048
	ds_read_b128 v[194:197], v138 offset:3072
	v_lshl_add_u64 v[230:231], s[34:35], 0, v[134:135]
	s_add_i32 m0, s91, 0xc000
	ds_read_b128 v[198:201], v185
	ds_read_b128 v[202:205], v185 offset:1024
	ds_read_b128 v[206:209], v185 offset:2048
	ds_read_b128 v[210:213], v185 offset:3072
	ds_read_b128 v[214:217], v185 offset:4096
	ds_read_b128 v[218:221], v185 offset:5120
	ds_read_b128 v[222:225], v185 offset:6144
	ds_read_b128 v[226:229], v185 offset:7168
	global_load_lds_dwordx4 v[230:231], off
	v_lshl_add_u64 v[230:231], s[34:35], 0, v[150:151]
	s_add_i32 m0, s91, 0xe000
	s_nop 0
	global_load_lds_dwordx4 v[230:231], off
	s_waitcnt lgkmcnt(8)
	s_barrier
	s_waitcnt lgkmcnt(0)
	v_mfma_f32_16x16x32_bf16 v[124:127], v[158:161], v[198:201], v[124:127]
	v_mfma_f32_16x16x32_bf16 v[120:123], v[190:193], v[198:201], v[120:123]
	v_mfma_f32_16x16x32_bf16 v[116:119], v[158:161], v[206:209], v[116:119]
	v_mfma_f32_16x16x32_bf16 v[112:115], v[190:193], v[206:209], v[112:115]
	v_mfma_f32_16x16x32_bf16 v[108:111], v[158:161], v[214:217], v[108:111]
	v_mfma_f32_16x16x32_bf16 v[104:107], v[190:193], v[214:217], v[104:107]
	v_mfma_f32_16x16x32_bf16 v[100:103], v[158:161], v[222:225], v[100:103]
	v_mfma_f32_16x16x32_bf16 v[96:99], v[190:193], v[222:225], v[96:99]
	v_mfma_f32_16x16x32_bf16 v[124:127], v[186:189], v[202:205], v[124:127]
	v_mfma_f32_16x16x32_bf16 v[120:123], v[194:197], v[202:205], v[120:123]
	v_mfma_f32_16x16x32_bf16 v[116:119], v[186:189], v[210:213], v[116:119]
	v_mfma_f32_16x16x32_bf16 v[112:115], v[194:197], v[210:213], v[112:115]
	v_mfma_f32_16x16x32_bf16 v[108:111], v[186:189], v[218:221], v[108:111]
	v_mfma_f32_16x16x32_bf16 v[104:107], v[194:197], v[218:221], v[104:107]
	v_mfma_f32_16x16x32_bf16 v[100:103], v[186:189], v[226:229], v[100:103]
	v_mfma_f32_16x16x32_bf16 v[96:99], v[194:197], v[226:229], v[96:99]
	s_barrier
	s_add_i32 vcc_lo, 0, 0x14000
	s_add_i32 s65, s65, s9
	v_add_u32_e32 v138, vcc_lo, v184
	s_mov_b32 m0, s65
	ds_read_b128 v[230:233], v138
	ds_read_b128 v[234:237], v138 offset:1024
	ds_read_b128 v[238:241], v138 offset:2048
	ds_read_b128 v[242:245], v138 offset:3072
	global_load_lds_dwordx4 v136, s[92:93]
	s_add_i32 m0, s65, 0x2000
	v_mov_b32_e32 v157, v137
	global_load_lds_dwordx4 v156, s[92:93]
	v_lshl_add_u64 v[246:247], s[92:93], 0, v[136:137]
	v_lshl_add_u64 v[248:249], s[92:93], 0, v[156:157]
	s_mov_b32 m0, s91
	v_lshl_add_u64 v[250:251], s[54:55], 0, v[154:155]
	s_waitcnt lgkmcnt(0)
	s_barrier
	v_mfma_f32_16x16x32_bf16 v[92:95], v[230:233], v[198:201], v[92:95]
	v_mfma_f32_16x16x32_bf16 v[88:91], v[238:241], v[198:201], v[88:91]
	v_mfma_f32_16x16x32_bf16 v[84:87], v[230:233], v[206:209], v[84:87]
	v_mfma_f32_16x16x32_bf16 v[80:83], v[238:241], v[206:209], v[80:83]
	v_mfma_f32_16x16x32_bf16 v[76:79], v[230:233], v[214:217], v[76:79]
	v_mfma_f32_16x16x32_bf16 v[72:75], v[238:241], v[214:217], v[72:75]
	v_mfma_f32_16x16x32_bf16 v[68:71], v[230:233], v[222:225], v[68:71]
	v_mfma_f32_16x16x32_bf16 v[64:67], v[238:241], v[222:225], v[64:67]
	v_mfma_f32_16x16x32_bf16 v[92:95], v[234:237], v[202:205], v[92:95]
	v_mfma_f32_16x16x32_bf16 v[88:91], v[242:245], v[202:205], v[88:91]
	v_mfma_f32_16x16x32_bf16 v[84:87], v[234:237], v[210:213], v[84:87]
	v_mfma_f32_16x16x32_bf16 v[80:83], v[242:245], v[210:213], v[80:83]
	v_mfma_f32_16x16x32_bf16 v[76:79], v[234:237], v[218:221], v[76:79]
	v_mfma_f32_16x16x32_bf16 v[72:75], v[242:245], v[218:221], v[72:75]
	v_mfma_f32_16x16x32_bf16 v[68:71], v[234:237], v[226:229], v[68:71]
	v_mfma_f32_16x16x32_bf16 v[64:67], v[242:245], v[226:229], v[64:67]
	s_barrier
	ds_read_b128 v[198:201], v185 offset:16384
	ds_read_b128 v[202:205], v185 offset:17408
	ds_read_b128 v[206:209], v185 offset:18432
	ds_read_b128 v[210:213], v185 offset:19456
	ds_read_b128 v[214:217], v185 offset:20480
	ds_read_b128 v[218:221], v185 offset:21504
	ds_read_b128 v[222:225], v185 offset:22528
	ds_read_b128 v[226:229], v185 offset:23552
	global_load_lds_dwordx4 v[250:251], off
	v_lshl_add_u64 v[140:141], s[54:55], 0, v[152:153]
	s_mov_b32 m0, s50
	s_nop 0
	global_load_lds_dwordx4 v[140:141], off
	s_barrier
	s_waitcnt lgkmcnt(0)
	v_mfma_f32_16x16x32_bf16 v[60:63], v[158:161], v[198:201], v[60:63]
	v_mfma_f32_16x16x32_bf16 v[56:59], v[190:193], v[198:201], v[56:59]
	v_mfma_f32_16x16x32_bf16 v[52:55], v[158:161], v[206:209], v[52:55]
	v_mfma_f32_16x16x32_bf16 v[48:51], v[190:193], v[206:209], v[48:51]
	v_mfma_f32_16x16x32_bf16 v[44:47], v[158:161], v[214:217], v[44:47]
	v_mfma_f32_16x16x32_bf16 v[40:43], v[190:193], v[214:217], v[40:43]
	v_mfma_f32_16x16x32_bf16 v[36:39], v[158:161], v[222:225], v[36:39]
	v_mfma_f32_16x16x32_bf16 v[32:35], v[190:193], v[222:225], v[32:35]
	v_mfma_f32_16x16x32_bf16 v[60:63], v[186:189], v[202:205], v[60:63]
	v_mfma_f32_16x16x32_bf16 v[56:59], v[194:197], v[202:205], v[56:59]
	v_mfma_f32_16x16x32_bf16 v[52:55], v[186:189], v[210:213], v[52:55]
	v_mfma_f32_16x16x32_bf16 v[48:51], v[194:197], v[210:213], v[48:51]
	v_mfma_f32_16x16x32_bf16 v[44:47], v[186:189], v[218:221], v[44:47]
	v_mfma_f32_16x16x32_bf16 v[40:43], v[194:197], v[218:221], v[40:43]
	v_mfma_f32_16x16x32_bf16 v[36:39], v[186:189], v[226:229], v[36:39]
	v_mfma_f32_16x16x32_bf16 v[32:35], v[194:197], v[226:229], v[32:35]
	s_barrier
	s_add_u32 s88, s92, s88
	s_addc_u32 s89, s93, s89
	s_add_i32 s65, vcc_lo, s9
	s_mov_b32 m0, s65
	v_lshl_add_u64 v[160:161], s[88:89], 0, v[136:137]
	global_load_lds_dwordx4 v136, s[88:89]
	s_add_i32 m0, s65, 0x2000
	v_lshl_add_u64 v[138:139], s[88:89], 0, v[156:157]
	global_load_lds_dwordx4 v156, s[88:89]
	s_add_i32 s65, 0, 0x18000
	v_add_u32_e32 v136, s65, v184
	s_waitcnt vmcnt(6)
	s_barrier
; #define PG8_STAGE(bufoff, gbase, v0, v1) do { \
;         __builtin_amdgcn_global_load_lds((const unsigned*)((const char*)(gbase) + (v0)), (LAS unsigned*)(lds + (bufoff) + ldsw), 16, 0, 0); \
;         __builtin_amdgcn_global_load_lds((const unsigned*)((const char*)(gbase) + (v1)), (LAS unsigned*)(lds + (bufoff) + ldsw + 8192), 16, 0, 0); } while (0)
; #define PG8_LDA(dst, b, h) do { _Pragma("unroll") for (int m = 0; m < 4; ++m) _Pragma("unroll") for (int k = 0; k < 2; ++k) dst[m][k] = *(const LAS bf16x8*)(lds + PG8_SA(b, h) + aoff + m * 2048 + k * 1024); } while (0)
; #define PG8_LDB(dst, b, h) do { _Pragma("unroll") for (int n = 0; n < 2; ++n) _Pragma("unroll") for (int k = 0; k < 2; ++k) dst[n][k] = *(const LAS bf16x8*)(lds + PG8_SB(b, h) + boff + n * 2048 + k * 1024); } while (0)
; #define PG8_MMA(ai, bj, At, Bt) do { __builtin_amdgcn_s_setprio(1); _Pragma("unroll") for (int m = 0; m < 4; ++m) _Pragma("unroll") for (int n = 0; n < 2; ++n) _Pragma("unroll") for (int k = 0; k < 2; ++k) \
;         acc[ai][bj][m][n] = __builtin_amdgcn_mfma_f32_16x16x32_bf16(Bt[n][k], At[m][k], acc[ai][bj][m][n], 0, 0, 0); __builtin_amdgcn_s_setprio(0); } while (0)
; #define PG8_WAIT_V(n) asm volatile("s_waitcnt vmcnt(" #n ")" ::: "memory")
; #define PG8_WAIT_L(n) asm volatile("s_waitcnt lgkmcnt(" #n ")" ::: "memory")
; #define PG8_BAR __builtin_amdgcn_s_barrier()
; #define PG8_SCHED __builtin_amdgcn_sched_barrier(0)
; template <class Epi, class Sched>
; __device__ __forceinline__ void gemm_phase(LAS unsigned char* lds, const Sched& S, const Epi& E) {
;     ...
;             PG8_WAIT_V(6); PG8_BAR; PG8_MMA(1, 1, At, B1); PG8_BAR;
;             PG8_LDB(B0, 1, 0); PG8_SCHED; PG8_LDA(At, 1, 0); PG8_STAGE(PG8_SA(0, 1), a2 + xhA, xA0, xA1);
;             PG8_WAIT_L(8); PG8_BAR; PG8_WAIT_L(0); PG8_MMA(0, 0, At, B0); PG8_BAR; PG8_SCHED;
;             PG8_LDB(B1, 1, 1); PG8_STAGE(PG8_SB(1, 0), b3, xB0, xB1);
;             PG8_BAR; PG8_WAIT_L(0); PG8_MMA(0, 1, At, B1); PG8_BAR;
	v_mfma_f32_16x16x32_bf16 v[28:31], v[230:233], v[198:201], v[28:31]
	v_mfma_f32_16x16x32_bf16 v[24:27], v[238:241], v[198:201], v[24:27]
	v_mfma_f32_16x16x32_bf16 v[20:23], v[230:233], v[206:209], v[20:23]
	v_mfma_f32_16x16x32_bf16 v[16:19], v[238:241], v[206:209], v[16:19]
	v_mfma_f32_16x16x32_bf16 v[12:15], v[230:233], v[214:217], v[12:15]
	v_mfma_f32_16x16x32_bf16 v[8:11], v[238:241], v[214:217], v[8:11]
	v_mfma_f32_16x16x32_bf16 v[4:7], v[230:233], v[222:225], v[4:7]
	v_mfma_f32_16x16x32_bf16 v[0:3], v[238:241], v[222:225], v[0:3]
	v_mfma_f32_16x16x32_bf16 v[28:31], v[234:237], v[202:205], v[28:31]
	v_mfma_f32_16x16x32_bf16 v[24:27], v[242:245], v[202:205], v[24:27]
	v_mfma_f32_16x16x32_bf16 v[20:23], v[234:237], v[210:213], v[20:23]
	v_mfma_f32_16x16x32_bf16 v[16:19], v[242:245], v[210:213], v[16:19]
	v_mfma_f32_16x16x32_bf16 v[12:15], v[234:237], v[218:221], v[12:15]
	v_mfma_f32_16x16x32_bf16 v[8:11], v[242:245], v[218:221], v[8:11]
	v_mfma_f32_16x16x32_bf16 v[4:7], v[234:237], v[226:229], v[4:7]
	v_mfma_f32_16x16x32_bf16 v[0:3], v[242:245], v[226:229], v[0:3]
	s_barrier
	ds_read_b128 v[156:159], v136
	ds_read_b128 v[186:189], v136 offset:1024
	ds_read_b128 v[190:193], v136 offset:2048
	ds_read_b128 v[194:197], v136 offset:3072
	s_add_u32 s54, s54, s82
	s_addc_u32 s55, s55, s83
	s_mov_b32 m0, s51
	v_lshl_add_u64 v[154:155], s[54:55], 0, v[154:155]
	ds_read_b128 v[198:201], v185 offset:32768
	ds_read_b128 v[202:205], v185 offset:33792
	ds_read_b128 v[206:209], v185 offset:34816
	ds_read_b128 v[210:213], v185 offset:35840
	ds_read_b128 v[214:217], v185 offset:36864
	ds_read_b128 v[218:221], v185 offset:37888
	ds_read_b128 v[222:225], v185 offset:38912
	ds_read_b128 v[226:229], v185 offset:39936
	global_load_lds_dwordx4 v[154:155], off
	v_lshl_add_u64 v[152:153], s[54:55], 0, v[152:153]
	s_mov_b32 m0, s8
	s_nop 0
	global_load_lds_dwordx4 v[152:153], off
	s_waitcnt lgkmcnt(8)
	s_barrier
	s_waitcnt lgkmcnt(0)
	v_mfma_f32_16x16x32_bf16 v[124:127], v[156:159], v[198:201], v[124:127]
	v_mfma_f32_16x16x32_bf16 v[120:123], v[190:193], v[198:201], v[120:123]
	v_mfma_f32_16x16x32_bf16 v[116:119], v[156:159], v[206:209], v[116:119]
	v_mfma_f32_16x16x32_bf16 v[112:115], v[190:193], v[206:209], v[112:115]
	v_mfma_f32_16x16x32_bf16 v[108:111], v[156:159], v[214:217], v[108:111]
	v_mfma_f32_16x16x32_bf16 v[104:107], v[190:193], v[214:217], v[104:107]
	v_mfma_f32_16x16x32_bf16 v[100:103], v[156:159], v[222:225], v[100:103]
	v_mfma_f32_16x16x32_bf16 v[96:99], v[190:193], v[222:225], v[96:99]
	v_mfma_f32_16x16x32_bf16 v[124:127], v[186:189], v[202:205], v[124:127]
	v_mfma_f32_16x16x32_bf16 v[120:123], v[194:197], v[202:205], v[120:123]
	v_mfma_f32_16x16x32_bf16 v[116:119], v[186:189], v[210:213], v[116:119]
	v_mfma_f32_16x16x32_bf16 v[112:115], v[194:197], v[210:213], v[112:115]
	v_mfma_f32_16x16x32_bf16 v[108:111], v[186:189], v[218:221], v[108:111]
	v_mfma_f32_16x16x32_bf16 v[104:107], v[194:197], v[218:221], v[104:107]
	v_mfma_f32_16x16x32_bf16 v[100:103], v[186:189], v[226:229], v[100:103]
	v_mfma_f32_16x16x32_bf16 v[96:99], v[194:197], v[226:229], v[96:99]
	s_barrier
	s_add_i32 s54, 0, 0x1c000
	s_add_i32 s55, s65, s9
	v_add_u32_e32 v136, s54, v184
	v_lshl_add_u64 v[242:243], v[246:247], 0, s[44:45]
	s_mov_b32 m0, s55
	ds_read_b128 v[152:155], v136
	ds_read_b128 v[230:233], v136 offset:1024
	ds_read_b128 v[234:237], v136 offset:2048
	ds_read_b128 v[238:241], v136 offset:3072
	global_load_lds_dwordx4 v[242:243], off
	v_lshl_add_u64 v[242:243], v[248:249], 0, s[44:45]
	s_add_i32 m0, s55, 0x2000
	s_nop 0
	global_load_lds_dwordx4 v[242:243], off
	s_mov_b32 m0, s21
	v_lshl_add_u64 v[242:243], v[250:251], 0, s[44:45]
	s_waitcnt lgkmcnt(0)
	s_barrier
	v_mfma_f32_16x16x32_bf16 v[92:95], v[152:155], v[198:201], v[92:95]
	v_mfma_f32_16x16x32_bf16 v[88:91], v[234:237], v[198:201], v[88:91]
	v_mfma_f32_16x16x32_bf16 v[84:87], v[152:155], v[206:209], v[84:87]
	v_mfma_f32_16x16x32_bf16 v[80:83], v[234:237], v[206:209], v[80:83]
	v_mfma_f32_16x16x32_bf16 v[76:79], v[152:155], v[214:217], v[76:79]
	v_mfma_f32_16x16x32_bf16 v[72:75], v[234:237], v[214:217], v[72:75]
	v_mfma_f32_16x16x32_bf16 v[68:71], v[152:155], v[222:225], v[68:71]
	v_mfma_f32_16x16x32_bf16 v[64:67], v[234:237], v[222:225], v[64:67]
	v_mfma_f32_16x16x32_bf16 v[92:95], v[230:233], v[202:205], v[92:95]
	v_mfma_f32_16x16x32_bf16 v[88:91], v[238:241], v[202:205], v[88:91]
	v_mfma_f32_16x16x32_bf16 v[84:87], v[230:233], v[210:213], v[84:87]
	v_mfma_f32_16x16x32_bf16 v[80:83], v[238:241], v[210:213], v[80:83]
	v_mfma_f32_16x16x32_bf16 v[76:79], v[230:233], v[218:221], v[76:79]
	v_mfma_f32_16x16x32_bf16 v[72:75], v[238:241], v[218:221], v[72:75]
	v_mfma_f32_16x16x32_bf16 v[68:71], v[230:233], v[226:229], v[68:71]
	v_mfma_f32_16x16x32_bf16 v[64:67], v[238:241], v[226:229], v[64:67]
	s_barrier
; #define PG8_STAGE(bufoff, gbase, v0, v1) do { \
;         __builtin_amdgcn_global_load_lds((const unsigned*)((const char*)(gbase) + (v0)), (LAS unsigned*)(lds + (bufoff) + ldsw), 16, 0, 0); \
;         __builtin_amdgcn_global_load_lds((const unsigned*)((const char*)(gbase) + (v1)), (LAS unsigned*)(lds + (bufoff) + ldsw + 8192), 16, 0, 0); } while (0)
; #define PG8_LDA(dst, b, h) do { _Pragma("unroll") for (int m = 0; m < 4; ++m) _Pragma("unroll") for (int k = 0; k < 2; ++k) dst[m][k] = *(const LAS bf16x8*)(lds + PG8_SA(b, h) + aoff + m * 2048 + k * 1024); } while (0)
; #define PG8_MMA(ai, bj, At, Bt) do { __builtin_amdgcn_s_setprio(1); _Pragma("unroll") for (int m = 0; m < 4; ++m) _Pragma("unroll") for (int n = 0; n < 2; ++n) _Pragma("unroll") for (int k = 0; k < 2; ++k) \
;         acc[ai][bj][m][n] = __builtin_amdgcn_mfma_f32_16x16x32_bf16(Bt[n][k], At[m][k], acc[ai][bj][m][n], 0, 0, 0); __builtin_amdgcn_s_setprio(0); } while (0)
; #define PG8_WAIT_V(n) asm volatile("s_waitcnt vmcnt(" #n ")" ::: "memory")
; #define PG8_WAIT_L(n) asm volatile("s_waitcnt lgkmcnt(" #n ")" ::: "memory")
; #define PG8_BAR __builtin_amdgcn_s_barrier()
; #define PG8_SCHED __builtin_amdgcn_sched_barrier(0)
; template <class Epi, class Sched>
; __device__ __forceinline__ void gemm_phase(LAS unsigned char* lds, const Sched& S, const Epi& E) {
;     ...
;         for (int t = 0; t < nt; t += 2) {
;             const bool last = (t == nt - 2);
;             const char* a1 = cA + (size_t)(t + 1) * kstep;
;             const char* a2 = last ? nA : cA + (size_t)(t + 2) * kstep; const char* b2 = last ? nB : cB + (size_t)(t + 2) * kstep;
;             const char* a3 = a2 + kstep; const char* b3 = b2 + kstep;
;             const unsigned xA0 = last ? nvA0 : vA0, xA1 = last ? nvA1 : vA1, xB0 = last ? nvB0 : vB0, xB1 = last ? nvB1 : vB1;
;     ...
;             PG8_LDA(At, 1, 1); PG8_STAGE(PG8_SA(1, 0), a3, xA0, xA1);
;             PG8_BAR; PG8_WAIT_L(0); PG8_MMA(1, 0, At, B0); PG8_BAR; PG8_SCHED;
;             PG8_STAGE(PG8_SB(1, 1), b3 + xhB, xB0, xB1);
;             PG8_WAIT_V(6); PG8_BAR; PG8_MMA(1, 1, At, B1); PG8_BAR;
	ds_read_b128 v[198:201], v185 offset:49152
	ds_read_b128 v[202:205], v185 offset:50176
	ds_read_b128 v[206:209], v185 offset:51200
	ds_read_b128 v[210:213], v185 offset:52224
	ds_read_b128 v[214:217], v185 offset:53248
	ds_read_b128 v[218:221], v185 offset:54272
	ds_read_b128 v[222:225], v185 offset:55296
	ds_read_b128 v[226:229], v185 offset:56320
	global_load_lds_dwordx4 v[242:243], off
	v_lshl_add_u64 v[140:141], v[140:141], 0, s[44:45]
	s_mov_b32 m0, s24
	s_nop 0
	global_load_lds_dwordx4 v[140:141], off
	s_barrier
	s_waitcnt lgkmcnt(0)
	v_mfma_f32_16x16x32_bf16 v[60:63], v[156:159], v[198:201], v[60:63]
	v_mfma_f32_16x16x32_bf16 v[56:59], v[190:193], v[198:201], v[56:59]
	v_mfma_f32_16x16x32_bf16 v[52:55], v[156:159], v[206:209], v[52:55]
	v_mfma_f32_16x16x32_bf16 v[48:51], v[190:193], v[206:209], v[48:51]
	v_mfma_f32_16x16x32_bf16 v[44:47], v[156:159], v[214:217], v[44:47]
	v_mfma_f32_16x16x32_bf16 v[40:43], v[190:193], v[214:217], v[40:43]
	v_mfma_f32_16x16x32_bf16 v[36:39], v[156:159], v[222:225], v[36:39]
	v_mfma_f32_16x16x32_bf16 v[32:35], v[190:193], v[222:225], v[32:35]
	v_mfma_f32_16x16x32_bf16 v[60:63], v[186:189], v[202:205], v[60:63]
	v_mfma_f32_16x16x32_bf16 v[56:59], v[194:197], v[202:205], v[56:59]
	v_mfma_f32_16x16x32_bf16 v[52:55], v[186:189], v[210:213], v[52:55]
	v_mfma_f32_16x16x32_bf16 v[48:51], v[194:197], v[210:213], v[48:51]
	v_mfma_f32_16x16x32_bf16 v[44:47], v[186:189], v[218:221], v[44:47]
	v_mfma_f32_16x16x32_bf16 v[40:43], v[194:197], v[218:221], v[40:43]
	v_mfma_f32_16x16x32_bf16 v[36:39], v[186:189], v[226:229], v[36:39]
	v_mfma_f32_16x16x32_bf16 v[32:35], v[194:197], v[226:229], v[32:35]
	s_barrier
	s_add_i32 s54, s54, s9
	v_lshl_add_u64 v[140:141], v[160:161], 0, s[44:45]
	s_mov_b32 m0, s54
	v_lshl_add_u64 v[138:139], v[138:139], 0, s[44:45]
	global_load_lds_dwordx4 v[140:141], off
	s_add_i32 m0, s54, 0x2000
	s_nop 0
	global_load_lds_dwordx4 v[138:139], off
	s_add_u32 s34, s34, 0x100
	s_addc_u32 s35, s35, 0
	s_add_u32 s70, s70, 0x100
	s_addc_u32 s71, s71, 0
	s_waitcnt vmcnt(6)
	s_barrier
	v_mfma_f32_16x16x32_bf16 v[28:31], v[152:155], v[198:201], v[28:31]
	v_mfma_f32_16x16x32_bf16 v[24:27], v[234:237], v[198:201], v[24:27]
	v_mfma_f32_16x16x32_bf16 v[20:23], v[152:155], v[206:209], v[20:23]
	v_mfma_f32_16x16x32_bf16 v[16:19], v[234:237], v[206:209], v[16:19]
	v_mfma_f32_16x16x32_bf16 v[12:15], v[152:155], v[214:217], v[12:15]
	v_mfma_f32_16x16x32_bf16 v[8:11], v[234:237], v[214:217], v[8:11]
	v_mfma_f32_16x16x32_bf16 v[4:7], v[152:155], v[222:225], v[4:7]
	v_mfma_f32_16x16x32_bf16 v[0:3], v[234:237], v[222:225], v[0:3]
	v_mfma_f32_16x16x32_bf16 v[28:31], v[230:233], v[202:205], v[28:31]
	v_mfma_f32_16x16x32_bf16 v[24:27], v[238:241], v[202:205], v[24:27]
	v_mfma_f32_16x16x32_bf16 v[20:23], v[230:233], v[210:213], v[20:23]
	v_mfma_f32_16x16x32_bf16 v[16:19], v[238:241], v[210:213], v[16:19]
	v_mfma_f32_16x16x32_bf16 v[12:15], v[230:233], v[218:221], v[12:15]
	v_mfma_f32_16x16x32_bf16 v[8:11], v[238:241], v[218:221], v[8:11]
	v_mfma_f32_16x16x32_bf16 v[4:7], v[230:233], v[226:229], v[4:7]
	v_mfma_f32_16x16x32_bf16 v[0:3], v[238:241], v[226:229], v[0:3]
	s_cmp_ge_i32 s49, s36
	s_cbranch_scc1 .Lrot_exit_1
	s_cmp_eq_u32 s39, s49
	s_cselect_b64 s[54:55], -1, 0
	s_and_b64 vcc, exec, s[54:55]
	v_mov_b64_e32 v[152:153], v[144:145]
	v_mov_b64_e32 v[154:155], v[142:143]
	s_mov_b64 s[88:89], s[68:69]
	s_mov_b64 s[82:83], s[66:67]
	v_mov_b32_e32 v156, v148
	v_mov_b32_e32 v136, v146
	s_mov_b64 s[92:93], s[42:43]
	s_cbranch_vccnz .Lrot_join_1
	v_mov_b64_e32 v[152:153], v[128:129]
	v_mov_b64_e32 v[154:155], v[132:133]
	s_mov_b64 s[88:89], s[12:13]
	s_mov_b64 s[82:83], s[14:15]
	v_mov_b32_e32 v156, v130
	v_mov_b32_e32 v136, v131
	s_mov_b64 s[92:93], s[70:71]

; #define PG8_STAGE(bufoff, gbase, v0, v1) do { \
;         __builtin_amdgcn_global_load_lds((const unsigned*)((const char*)(gbase) + (v0)), (LAS unsigned*)(lds + (bufoff) + ldsw), 16, 0, 0); \
;         __builtin_amdgcn_global_load_lds((const unsigned*)((const char*)(gbase) + (v1)), (LAS unsigned*)(lds + (bufoff) + ldsw + 8192), 16, 0, 0); } while (0)
; #define PG8_LDA(dst, b, h) do { _Pragma("unroll") for (int m = 0; m < 4; ++m) _Pragma("unroll") for (int k = 0; k < 2; ++k) dst[m][k] = *(const LAS bf16x8*)(lds + PG8_SA(b, h) + aoff + m * 2048 + k * 1024); } while (0)
; #define PG8_LDB(dst, b, h) do { _Pragma("unroll") for (int n = 0; n < 2; ++n) _Pragma("unroll") for (int k = 0; k < 2; ++k) dst[n][k] = *(const LAS bf16x8*)(lds + PG8_SB(b, h) + boff + n * 2048 + k * 1024); } while (0)
; #define PG8_MMA(ai, bj, At, Bt) do { __builtin_amdgcn_s_setprio(1); _Pragma("unroll") for (int m = 0; m < 4; ++m) _Pragma("unroll") for (int n = 0; n < 2; ++n) _Pragma("unroll") for (int k = 0; k < 2; ++k) \
;         acc[ai][bj][m][n] = __builtin_amdgcn_mfma_f32_16x16x32_bf16(Bt[n][k], At[m][k], acc[ai][bj][m][n], 0, 0, 0); __builtin_amdgcn_s_setprio(0); } while (0)
; #define PG8_WAIT_V(n) asm volatile("s_waitcnt vmcnt(" #n ")" ::: "memory")
; #define PG8_WAIT_L(n) asm volatile("s_waitcnt lgkmcnt(" #n ")" ::: "memory")
; #define PG8_BAR __builtin_amdgcn_s_barrier()
; #define PG8_SCHED __builtin_amdgcn_sched_barrier(0)
; template <class Epi, class Sched>
; __device__ __forceinline__ void gemm_phase(LAS unsigned char* lds, const Sched& S, const Epi& E) {
;     ...
;             PG8_LDB(B0, 0, 0); PG8_SCHED; PG8_LDA(At, 0, 0); PG8_STAGE(PG8_SA(1, 1), a1 + hA, vA0, vA1);
;             PG8_WAIT_L(8); PG8_BAR; PG8_WAIT_L(0); PG8_MMA(0, 0, At, B0); PG8_BAR; PG8_SCHED;
;             PG8_LDB(B1, 0, 1); PG8_STAGE(PG8_SB(0, 0), b2, xB0, xB1);
;             PG8_BAR; PG8_WAIT_L(0); PG8_MMA(0, 1, At, B1); PG8_BAR;
;             PG8_LDA(At, 0, 1); PG8_STAGE(PG8_SA(0, 0), a2, xA0, xA1);
;             PG8_BAR; PG8_WAIT_L(0); PG8_MMA(1, 0, At, B0); PG8_BAR; PG8_SCHED;
;             PG8_STAGE(PG8_SB(0, 1), b2 + xhB, xB0, xB1);
;             PG8_WAIT_V(6); PG8_BAR; PG8_MMA(1, 1, At, B1); PG8_BAR;
;             PG8_LDB(B0, 1, 0); PG8_SCHED; PG8_LDA(At, 1, 0); PG8_STAGE(PG8_SA(0, 1), a2 + xhA, xA0, xA1);
.Lrot_body_2:
	ds_read_b128 v[150:153], v138
	ds_read_b128 v[154:157], v138 offset:1024
	ds_read_b128 v[158:161], v138 offset:2048
	ds_read_b128 v[182:185], v138 offset:3072
	v_lshl_add_u64 v[138:139], s[34:35], 0, v[136:137]
	s_add_i32 m0, s50, 0xc000
	ds_read_b128 v[186:189], v148
	ds_read_b128 v[190:193], v148 offset:1024
	ds_read_b128 v[194:197], v148 offset:2048
	ds_read_b128 v[198:201], v148 offset:3072
	ds_read_b128 v[202:205], v148 offset:4096
	ds_read_b128 v[206:209], v148 offset:5120
	ds_read_b128 v[210:213], v148 offset:6144
	ds_read_b128 v[214:217], v148 offset:7168
	global_load_lds_dwordx4 v[138:139], off
	v_lshl_add_u64 v[138:139], s[34:35], 0, v[132:133]
	s_add_i32 m0, s50, 0xe000
	s_nop 0
	global_load_lds_dwordx4 v[138:139], off
	s_waitcnt lgkmcnt(8)
	s_barrier
	s_waitcnt lgkmcnt(0)
	v_mfma_f32_16x16x32_bf16 v[124:127], v[150:153], v[186:189], v[124:127]
	v_mfma_f32_16x16x32_bf16 v[120:123], v[158:161], v[186:189], v[120:123]
	v_mfma_f32_16x16x32_bf16 v[108:111], v[150:153], v[194:197], v[108:111]
	v_mfma_f32_16x16x32_bf16 v[104:107], v[158:161], v[194:197], v[104:107]
	v_mfma_f32_16x16x32_bf16 v[92:95], v[150:153], v[202:205], v[92:95]
	v_mfma_f32_16x16x32_bf16 v[88:91], v[158:161], v[202:205], v[88:91]
	v_mfma_f32_16x16x32_bf16 v[76:79], v[150:153], v[210:213], v[76:79]
	v_mfma_f32_16x16x32_bf16 v[72:75], v[158:161], v[210:213], v[72:75]
	v_mfma_f32_16x16x32_bf16 v[124:127], v[154:157], v[190:193], v[124:127]
	v_mfma_f32_16x16x32_bf16 v[120:123], v[182:185], v[190:193], v[120:123]
	v_mfma_f32_16x16x32_bf16 v[108:111], v[154:157], v[198:201], v[108:111]
	v_mfma_f32_16x16x32_bf16 v[104:107], v[182:185], v[198:201], v[104:107]
	v_mfma_f32_16x16x32_bf16 v[92:95], v[154:157], v[206:209], v[92:95]
	v_mfma_f32_16x16x32_bf16 v[88:91], v[182:185], v[206:209], v[88:91]
	v_mfma_f32_16x16x32_bf16 v[76:79], v[154:157], v[214:217], v[76:79]
	v_mfma_f32_16x16x32_bf16 v[72:75], v[182:185], v[214:217], v[72:75]
	s_barrier
	s_add_i32 s71, 0, 0x14000
	v_add_u32_e32 v138, s71, v147
	s_add_i32 s23, s23, s49
	ds_read_b128 v[218:221], v138
	ds_read_b128 v[222:225], v138 offset:1024
	ds_read_b128 v[226:229], v138 offset:2048
	ds_read_b128 v[230:233], v138 offset:3072
	v_lshl_add_u64 v[138:139], s[40:41], 0, v[142:143]
	s_mov_b32 m0, s23
	v_lshl_add_u64 v[140:141], s[40:41], 0, v[134:135]
	global_load_lds_dwordx4 v[138:139], off
	s_add_i32 m0, s23, 0x2000
	s_nop 0
	global_load_lds_dwordx4 v[140:141], off
	s_mov_b32 m0, s50
	v_lshl_add_u64 v[234:235], s[42:43], 0, v[142:143]
	s_waitcnt lgkmcnt(0)
	s_barrier
	v_mfma_f32_16x16x32_bf16 v[116:119], v[218:221], v[186:189], v[116:119]
	v_mfma_f32_16x16x32_bf16 v[112:115], v[226:229], v[186:189], v[112:115]
	v_mfma_f32_16x16x32_bf16 v[100:103], v[218:221], v[194:197], v[100:103]
	v_mfma_f32_16x16x32_bf16 v[96:99], v[226:229], v[194:197], v[96:99]
	v_mfma_f32_16x16x32_bf16 v[84:87], v[218:221], v[202:205], v[84:87]
	v_mfma_f32_16x16x32_bf16 v[80:83], v[226:229], v[202:205], v[80:83]
	v_mfma_f32_16x16x32_bf16 v[68:71], v[218:221], v[210:213], v[68:71]
	v_mfma_f32_16x16x32_bf16 v[64:67], v[226:229], v[210:213], v[64:67]
	v_mfma_f32_16x16x32_bf16 v[116:119], v[222:225], v[190:193], v[116:119]
	v_mfma_f32_16x16x32_bf16 v[112:115], v[230:233], v[190:193], v[112:115]
	v_mfma_f32_16x16x32_bf16 v[100:103], v[222:225], v[198:201], v[100:103]
	v_mfma_f32_16x16x32_bf16 v[96:99], v[230:233], v[198:201], v[96:99]
	v_mfma_f32_16x16x32_bf16 v[84:87], v[222:225], v[206:209], v[84:87]
	v_mfma_f32_16x16x32_bf16 v[80:83], v[230:233], v[206:209], v[80:83]
	v_mfma_f32_16x16x32_bf16 v[68:71], v[222:225], v[214:217], v[68:71]
	v_mfma_f32_16x16x32_bf16 v[64:67], v[230:233], v[214:217], v[64:67]
	s_barrier
	ds_read_b128 v[186:189], v148 offset:16384
	ds_read_b128 v[190:193], v148 offset:17408
	ds_read_b128 v[194:197], v148 offset:18432
	ds_read_b128 v[198:201], v148 offset:19456
	ds_read_b128 v[202:205], v148 offset:20480
	ds_read_b128 v[206:209], v148 offset:21504
	ds_read_b128 v[210:213], v148 offset:22528
	ds_read_b128 v[214:217], v148 offset:23552
	global_load_lds_dwordx4 v[234:235], off
	v_lshl_add_u64 v[236:237], s[42:43], 0, v[134:135]
	s_mov_b32 m0, s51
	s_nop 0
	global_load_lds_dwordx4 v[236:237], off
	s_barrier
	s_waitcnt lgkmcnt(0)
	v_mfma_f32_16x16x32_bf16 v[60:63], v[150:153], v[186:189], v[60:63]
	v_mfma_f32_16x16x32_bf16 v[56:59], v[158:161], v[186:189], v[56:59]
	v_mfma_f32_16x16x32_bf16 v[44:47], v[150:153], v[194:197], v[44:47]
	v_mfma_f32_16x16x32_bf16 v[40:43], v[158:161], v[194:197], v[40:43]
	v_mfma_f32_16x16x32_bf16 v[28:31], v[150:153], v[202:205], v[28:31]
	v_mfma_f32_16x16x32_bf16 v[24:27], v[158:161], v[202:205], v[24:27]
	v_mfma_f32_16x16x32_bf16 v[12:15], v[150:153], v[210:213], v[12:15]
	v_mfma_f32_16x16x32_bf16 v[8:11], v[158:161], v[210:213], v[8:11]
	v_mfma_f32_16x16x32_bf16 v[60:63], v[154:157], v[190:193], v[60:63]
	v_mfma_f32_16x16x32_bf16 v[56:59], v[182:185], v[190:193], v[56:59]
	v_mfma_f32_16x16x32_bf16 v[44:47], v[154:157], v[198:201], v[44:47]
	v_mfma_f32_16x16x32_bf16 v[40:43], v[182:185], v[198:201], v[40:43]
	v_mfma_f32_16x16x32_bf16 v[28:31], v[154:157], v[206:209], v[28:31]
	v_mfma_f32_16x16x32_bf16 v[24:27], v[182:185], v[206:209], v[24:27]
	v_mfma_f32_16x16x32_bf16 v[12:15], v[154:157], v[214:217], v[12:15]
	v_mfma_f32_16x16x32_bf16 v[8:11], v[182:185], v[214:217], v[8:11]
	s_barrier
	s_add_u32 s82, s40, 0x80000
	s_addc_u32 s83, s41, 0
	s_add_i32 s23, s71, s49
	v_lshl_add_u64 v[150:151], s[82:83], 0, v[142:143]
	s_mov_b32 m0, s23
	s_nop 0
	global_load_lds_dwordx4 v[150:151], off
	v_lshl_add_u64 v[150:151], s[82:83], 0, v[134:135]
	s_add_i32 m0, s23, 0x2000
	s_nop 0
	global_load_lds_dwordx4 v[150:151], off
	s_add_i32 s23, 0, 0x18000
	v_add_u32_e32 v149, s23, v147
	s_waitcnt vmcnt(6)
	s_barrier
; #define PG8_STAGE(bufoff, gbase, v0, v1) do { \
;         __builtin_amdgcn_global_load_lds((const unsigned*)((const char*)(gbase) + (v0)), (LAS unsigned*)(lds + (bufoff) + ldsw), 16, 0, 0); \
;         __builtin_amdgcn_global_load_lds((const unsigned*)((const char*)(gbase) + (v1)), (LAS unsigned*)(lds + (bufoff) + ldsw + 8192), 16, 0, 0); } while (0)
; #define PG8_LDA(dst, b, h) do { _Pragma("unroll") for (int m = 0; m < 4; ++m) _Pragma("unroll") for (int k = 0; k < 2; ++k) dst[m][k] = *(const LAS bf16x8*)(lds + PG8_SA(b, h) + aoff + m * 2048 + k * 1024); } while (0)
; #define PG8_LDB(dst, b, h) do { _Pragma("unroll") for (int n = 0; n < 2; ++n) _Pragma("unroll") for (int k = 0; k < 2; ++k) dst[n][k] = *(const LAS bf16x8*)(lds + PG8_SB(b, h) + boff + n * 2048 + k * 1024); } while (0)
; #define PG8_MMA(ai, bj, At, Bt) do { __builtin_amdgcn_s_setprio(1); _Pragma("unroll") for (int m = 0; m < 4; ++m) _Pragma("unroll") for (int n = 0; n < 2; ++n) _Pragma("unroll") for (int k = 0; k < 2; ++k) \
;         acc[ai][bj][m][n] = __builtin_amdgcn_mfma_f32_16x16x32_bf16(Bt[n][k], At[m][k], acc[ai][bj][m][n], 0, 0, 0); __builtin_amdgcn_s_setprio(0); } while (0)
; #define PG8_WAIT_V(n) asm volatile("s_waitcnt vmcnt(" #n ")" ::: "memory")
; #define PG8_WAIT_L(n) asm volatile("s_waitcnt lgkmcnt(" #n ")" ::: "memory")
; #define PG8_BAR __builtin_amdgcn_s_barrier()
; #define PG8_SCHED __builtin_amdgcn_sched_barrier(0)
; template <class Epi, class Sched>
; __device__ __forceinline__ void gemm_phase(LAS unsigned char* lds, const Sched& S, const Epi& E) {
;     ...
;             PG8_WAIT_V(6); PG8_BAR; PG8_MMA(1, 1, At, B1); PG8_BAR;
;             PG8_LDB(B0, 1, 0); PG8_SCHED; PG8_LDA(At, 1, 0); PG8_STAGE(PG8_SA(0, 1), a2 + xhA, xA0, xA1);
;             PG8_WAIT_L(8); PG8_BAR; PG8_WAIT_L(0); PG8_MMA(0, 0, At, B0); PG8_BAR; PG8_SCHED;
;             PG8_LDB(B1, 1, 1); PG8_STAGE(PG8_SB(1, 0), b3, xB0, xB1);
;             PG8_BAR; PG8_WAIT_L(0); PG8_MMA(0, 1, At, B1); PG8_BAR;
	v_mfma_f32_16x16x32_bf16 v[52:55], v[218:221], v[186:189], v[52:55]
	v_mfma_f32_16x16x32_bf16 v[48:51], v[226:229], v[186:189], v[48:51]
	v_mfma_f32_16x16x32_bf16 v[36:39], v[218:221], v[194:197], v[36:39]
	v_mfma_f32_16x16x32_bf16 v[32:35], v[226:229], v[194:197], v[32:35]
	v_mfma_f32_16x16x32_bf16 v[20:23], v[218:221], v[202:205], v[20:23]
	v_mfma_f32_16x16x32_bf16 v[16:19], v[226:229], v[202:205], v[16:19]
	v_mfma_f32_16x16x32_bf16 v[4:7], v[218:221], v[210:213], v[4:7]
	v_mfma_f32_16x16x32_bf16 v[0:3], v[226:229], v[210:213], v[0:3]
	v_mfma_f32_16x16x32_bf16 v[52:55], v[222:225], v[190:193], v[52:55]
	v_mfma_f32_16x16x32_bf16 v[48:51], v[230:233], v[190:193], v[48:51]
	v_mfma_f32_16x16x32_bf16 v[36:39], v[222:225], v[198:201], v[36:39]
	v_mfma_f32_16x16x32_bf16 v[32:35], v[230:233], v[198:201], v[32:35]
	v_mfma_f32_16x16x32_bf16 v[20:23], v[222:225], v[206:209], v[20:23]
	v_mfma_f32_16x16x32_bf16 v[16:19], v[230:233], v[206:209], v[16:19]
	v_mfma_f32_16x16x32_bf16 v[4:7], v[222:225], v[214:217], v[4:7]
	v_mfma_f32_16x16x32_bf16 v[0:3], v[230:233], v[214:217], v[0:3]
	s_barrier
	ds_read_b128 v[150:153], v149
	ds_read_b128 v[154:157], v149 offset:1024
	ds_read_b128 v[158:161], v149 offset:2048
	ds_read_b128 v[182:185], v149 offset:3072
	s_add_u32 s42, s42, 0x80000
	s_addc_u32 s43, s43, 0
	s_mov_b32 m0, s54
	v_lshl_add_u64 v[218:219], s[42:43], 0, v[142:143]
	ds_read_b128 v[186:189], v148 offset:32768
	ds_read_b128 v[190:193], v148 offset:33792
	ds_read_b128 v[194:197], v148 offset:34816
	ds_read_b128 v[198:201], v148 offset:35840
	ds_read_b128 v[202:205], v148 offset:36864
	ds_read_b128 v[206:209], v148 offset:37888
	ds_read_b128 v[210:213], v148 offset:38912
	ds_read_b128 v[214:217], v148 offset:39936
	global_load_lds_dwordx4 v[218:219], off
	v_lshl_add_u64 v[218:219], s[42:43], 0, v[134:135]
	s_mov_b32 m0, s55
	s_nop 0
	global_load_lds_dwordx4 v[218:219], off
	s_waitcnt lgkmcnt(8)
	s_barrier
	s_waitcnt lgkmcnt(0)
	v_mfma_f32_16x16x32_bf16 v[124:127], v[150:153], v[186:189], v[124:127]
	v_mfma_f32_16x16x32_bf16 v[120:123], v[158:161], v[186:189], v[120:123]
	v_mfma_f32_16x16x32_bf16 v[108:111], v[150:153], v[194:197], v[108:111]
	v_mfma_f32_16x16x32_bf16 v[104:107], v[158:161], v[194:197], v[104:107]
	v_mfma_f32_16x16x32_bf16 v[92:95], v[150:153], v[202:205], v[92:95]
	v_mfma_f32_16x16x32_bf16 v[88:91], v[158:161], v[202:205], v[88:91]
	v_mfma_f32_16x16x32_bf16 v[76:79], v[150:153], v[210:213], v[76:79]
	v_mfma_f32_16x16x32_bf16 v[72:75], v[158:161], v[210:213], v[72:75]
	v_mfma_f32_16x16x32_bf16 v[124:127], v[154:157], v[190:193], v[124:127]
	v_mfma_f32_16x16x32_bf16 v[120:123], v[182:185], v[190:193], v[120:123]
	v_mfma_f32_16x16x32_bf16 v[108:111], v[154:157], v[198:201], v[108:111]
	v_mfma_f32_16x16x32_bf16 v[104:107], v[182:185], v[198:201], v[104:107]
	v_mfma_f32_16x16x32_bf16 v[92:95], v[154:157], v[206:209], v[92:95]
	v_mfma_f32_16x16x32_bf16 v[88:91], v[182:185], v[206:209], v[88:91]
	v_mfma_f32_16x16x32_bf16 v[76:79], v[154:157], v[214:217], v[76:79]
	v_mfma_f32_16x16x32_bf16 v[72:75], v[182:185], v[214:217], v[72:75]
	s_barrier
	s_add_i32 s42, 0, 0x1c000
	s_add_i32 s23, s23, s49
	v_add_u32_e32 v149, s42, v147
	v_lshl_add_u64 v[138:139], v[138:139], 0, s[44:45]
	s_mov_b32 m0, s23
	ds_read_b128 v[218:221], v149
	ds_read_b128 v[222:225], v149 offset:1024
	ds_read_b128 v[226:229], v149 offset:2048
	ds_read_b128 v[230:233], v149 offset:3072
	global_load_lds_dwordx4 v[138:139], off
	v_lshl_add_u64 v[138:139], v[140:141], 0, s[44:45]
	s_add_i32 m0, s23, 0x2000
	s_nop 0
	global_load_lds_dwordx4 v[138:139], off
	s_mov_b32 m0, s66
	v_lshl_add_u64 v[138:139], v[234:235], 0, s[44:45]
	s_waitcnt lgkmcnt(0)
	s_barrier
; #define PG8_STAGE(bufoff, gbase, v0, v1) do { \
;         __builtin_amdgcn_global_load_lds((const unsigned*)((const char*)(gbase) + (v0)), (LAS unsigned*)(lds + (bufoff) + ldsw), 16, 0, 0); \
;         __builtin_amdgcn_global_load_lds((const unsigned*)((const char*)(gbase) + (v1)), (LAS unsigned*)(lds + (bufoff) + ldsw + 8192), 16, 0, 0); } while (0)
; #define PG8_LDA(dst, b, h) do { _Pragma("unroll") for (int m = 0; m < 4; ++m) _Pragma("unroll") for (int k = 0; k < 2; ++k) dst[m][k] = *(const LAS bf16x8*)(lds + PG8_SA(b, h) + aoff + m * 2048 + k * 1024); } while (0)
; #define PG8_MMA(ai, bj, At, Bt) do { __builtin_amdgcn_s_setprio(1); _Pragma("unroll") for (int m = 0; m < 4; ++m) _Pragma("unroll") for (int n = 0; n < 2; ++n) _Pragma("unroll") for (int k = 0; k < 2; ++k) \
;         acc[ai][bj][m][n] = __builtin_amdgcn_mfma_f32_16x16x32_bf16(Bt[n][k], At[m][k], acc[ai][bj][m][n], 0, 0, 0); __builtin_amdgcn_s_setprio(0); } while (0)
; #define PG8_WAIT_V(n) asm volatile("s_waitcnt vmcnt(" #n ")" ::: "memory")
; #define PG8_WAIT_L(n) asm volatile("s_waitcnt lgkmcnt(" #n ")" ::: "memory")
; #define PG8_BAR __builtin_amdgcn_s_barrier()
; #define PG8_SCHED __builtin_amdgcn_sched_barrier(0)
; template <class Epi, class Sched>
; __device__ __forceinline__ void gemm_phase(LAS unsigned char* lds, const Sched& S, const Epi& E) {
;     ...
;         for (int t = 0; t < nt; t += 2) {
;             const bool last = (t == nt - 2);
;             const char* a1 = cA + (size_t)(t + 1) * kstep;
;             const char* a2 = last ? nA : cA + (size_t)(t + 2) * kstep; const char* b2 = last ? nB : cB + (size_t)(t + 2) * kstep;
;             const char* a3 = a2 + kstep; const char* b3 = b2 + kstep;
;             const unsigned xA0 = last ? nvA0 : vA0, xA1 = last ? nvA1 : vA1, xB0 = last ? nvB0 : vB0, xB1 = last ? nvB1 : vB1;
;     ...
;             PG8_BAR; PG8_WAIT_L(0); PG8_MMA(0, 1, At, B1); PG8_BAR;
;             PG8_LDA(At, 1, 1); PG8_STAGE(PG8_SA(1, 0), a3, xA0, xA1);
;             PG8_BAR; PG8_WAIT_L(0); PG8_MMA(1, 0, At, B0); PG8_BAR; PG8_SCHED;
;             PG8_STAGE(PG8_SB(1, 1), b3 + xhB, xB0, xB1);
;             PG8_WAIT_V(6); PG8_BAR; PG8_MMA(1, 1, At, B1); PG8_BAR;
	v_mfma_f32_16x16x32_bf16 v[116:119], v[218:221], v[186:189], v[116:119]
	v_mfma_f32_16x16x32_bf16 v[112:115], v[226:229], v[186:189], v[112:115]
	v_mfma_f32_16x16x32_bf16 v[100:103], v[218:221], v[194:197], v[100:103]
	v_mfma_f32_16x16x32_bf16 v[96:99], v[226:229], v[194:197], v[96:99]
	v_mfma_f32_16x16x32_bf16 v[84:87], v[218:221], v[202:205], v[84:87]
	v_mfma_f32_16x16x32_bf16 v[80:83], v[226:229], v[202:205], v[80:83]
	v_mfma_f32_16x16x32_bf16 v[68:71], v[218:221], v[210:213], v[68:71]
	v_mfma_f32_16x16x32_bf16 v[64:67], v[226:229], v[210:213], v[64:67]
	v_mfma_f32_16x16x32_bf16 v[116:119], v[222:225], v[190:193], v[116:119]
	v_mfma_f32_16x16x32_bf16 v[112:115], v[230:233], v[190:193], v[112:115]
	v_mfma_f32_16x16x32_bf16 v[100:103], v[222:225], v[198:201], v[100:103]
	v_mfma_f32_16x16x32_bf16 v[96:99], v[230:233], v[198:201], v[96:99]
	v_mfma_f32_16x16x32_bf16 v[84:87], v[222:225], v[206:209], v[84:87]
	v_mfma_f32_16x16x32_bf16 v[80:83], v[230:233], v[206:209], v[80:83]
	v_mfma_f32_16x16x32_bf16 v[68:71], v[222:225], v[214:217], v[68:71]
	v_mfma_f32_16x16x32_bf16 v[64:67], v[230:233], v[214:217], v[64:67]
	s_barrier
	ds_read_b128 v[186:189], v148 offset:49152
	ds_read_b128 v[190:193], v148 offset:50176
	ds_read_b128 v[194:197], v148 offset:51200
	ds_read_b128 v[198:201], v148 offset:52224
	ds_read_b128 v[202:205], v148 offset:53248
	ds_read_b128 v[206:209], v148 offset:54272
	ds_read_b128 v[210:213], v148 offset:55296
	ds_read_b128 v[214:217], v148 offset:56320
	global_load_lds_dwordx4 v[138:139], off
	v_lshl_add_u64 v[138:139], v[236:237], 0, s[44:45]
	s_mov_b32 m0, s67
	s_nop 0
	global_load_lds_dwordx4 v[138:139], off
	s_barrier
	s_waitcnt lgkmcnt(0)
	v_mfma_f32_16x16x32_bf16 v[60:63], v[150:153], v[186:189], v[60:63]
	v_mfma_f32_16x16x32_bf16 v[56:59], v[158:161], v[186:189], v[56:59]
	v_mfma_f32_16x16x32_bf16 v[44:47], v[150:153], v[194:197], v[44:47]
	v_mfma_f32_16x16x32_bf16 v[40:43], v[158:161], v[194:197], v[40:43]
	v_mfma_f32_16x16x32_bf16 v[28:31], v[150:153], v[202:205], v[28:31]
	v_mfma_f32_16x16x32_bf16 v[24:27], v[158:161], v[202:205], v[24:27]
	v_mfma_f32_16x16x32_bf16 v[12:15], v[150:153], v[210:213], v[12:15]
	v_mfma_f32_16x16x32_bf16 v[8:11], v[158:161], v[210:213], v[8:11]
	v_mfma_f32_16x16x32_bf16 v[60:63], v[154:157], v[190:193], v[60:63]
	v_mfma_f32_16x16x32_bf16 v[56:59], v[182:185], v[190:193], v[56:59]
	v_mfma_f32_16x16x32_bf16 v[44:47], v[154:157], v[198:201], v[44:47]
	v_mfma_f32_16x16x32_bf16 v[40:43], v[182:185], v[198:201], v[40:43]
	v_mfma_f32_16x16x32_bf16 v[28:31], v[154:157], v[206:209], v[28:31]
	v_mfma_f32_16x16x32_bf16 v[24:27], v[182:185], v[206:209], v[24:27]
	v_mfma_f32_16x16x32_bf16 v[12:15], v[154:157], v[214:217], v[12:15]
	v_mfma_f32_16x16x32_bf16 v[8:11], v[182:185], v[214:217], v[8:11]
	s_barrier
	s_add_u32 s40, s40, 0x80080
	s_addc_u32 s41, s41, 0
	s_add_i32 s23, s42, s49
	v_lshl_add_u64 v[138:139], s[40:41], 0, v[142:143]
	s_mov_b32 m0, s23
	v_lshl_add_u64 v[134:135], s[40:41], 0, v[134:135]
	global_load_lds_dwordx4 v[138:139], off
	s_add_i32 m0, s23, 0x2000
	s_nop 0
	global_load_lds_dwordx4 v[134:135], off
	s_add_i32 s21, s21, 2
	s_add_u32 s34, s34, 0x100
	s_addc_u32 s35, s35, 0
	s_add_u32 s38, s38, 0x100
	s_addc_u32 s39, s39, 0
	s_waitcnt vmcnt(6)
	s_barrier
	v_mfma_f32_16x16x32_bf16 v[52:55], v[218:221], v[186:189], v[52:55]
	v_mfma_f32_16x16x32_bf16 v[48:51], v[226:229], v[186:189], v[48:51]
	v_mfma_f32_16x16x32_bf16 v[36:39], v[218:221], v[194:197], v[36:39]
	v_mfma_f32_16x16x32_bf16 v[32:35], v[226:229], v[194:197], v[32:35]
	v_mfma_f32_16x16x32_bf16 v[20:23], v[218:221], v[202:205], v[20:23]
	v_mfma_f32_16x16x32_bf16 v[16:19], v[226:229], v[202:205], v[16:19]
	v_mfma_f32_16x16x32_bf16 v[4:7], v[218:221], v[210:213], v[4:7]
	v_mfma_f32_16x16x32_bf16 v[0:3], v[226:229], v[210:213], v[0:3]
	v_mfma_f32_16x16x32_bf16 v[52:55], v[222:225], v[190:193], v[52:55]
	v_mfma_f32_16x16x32_bf16 v[48:51], v[230:233], v[190:193], v[48:51]
	v_mfma_f32_16x16x32_bf16 v[36:39], v[222:225], v[198:201], v[36:39]
	v_mfma_f32_16x16x32_bf16 v[32:35], v[230:233], v[198:201], v[32:35]
	v_mfma_f32_16x16x32_bf16 v[20:23], v[222:225], v[206:209], v[20:23]
	v_mfma_f32_16x16x32_bf16 v[16:19], v[230:233], v[206:209], v[16:19]
	v_mfma_f32_16x16x32_bf16 v[4:7], v[222:225], v[214:217], v[4:7]
	v_mfma_f32_16x16x32_bf16 v[0:3], v[230:233], v[214:217], v[0:3]
	s_cmp_gt_u32 s21, 29
	s_cbranch_scc1 .Lrot_exit_2
	s_cmp_eq_u32 s21, 28
	s_cselect_b64 s[42:43], -1, 0
	s_and_b64 vcc, exec, s[42:43]
	v_mov_b64_e32 v[134:135], v[130:131]
	v_mov_b64_e32 v[142:143], v[128:129]
	s_mov_b64 s[40:41], s[26:27]
	s_cbranch_vccnz .Lrot_join_2
	v_mov_b64_e32 v[134:135], v[132:133]
	v_mov_b64_e32 v[142:143], v[136:137]
	s_mov_b64 s[40:41], s[38:39]

; #define PG8_STAGE(bufoff, gbase, v0, v1) do { \
;         __builtin_amdgcn_global_load_lds((const unsigned*)((const char*)(gbase) + (v0)), (LAS unsigned*)(lds + (bufoff) + ldsw), 16, 0, 0); \
;         __builtin_amdgcn_global_load_lds((const unsigned*)((const char*)(gbase) + (v1)), (LAS unsigned*)(lds + (bufoff) + ldsw + 8192), 16, 0, 0); } while (0)
; #define PG8_LDA(dst, b, h) do { _Pragma("unroll") for (int m = 0; m < 4; ++m) _Pragma("unroll") for (int k = 0; k < 2; ++k) dst[m][k] = *(const LAS bf16x8*)(lds + PG8_SA(b, h) + aoff + m * 2048 + k * 1024); } while (0)
; #define PG8_LDB(dst, b, h) do { _Pragma("unroll") for (int n = 0; n < 2; ++n) _Pragma("unroll") for (int k = 0; k < 2; ++k) dst[n][k] = *(const LAS bf16x8*)(lds + PG8_SB(b, h) + boff + n * 2048 + k * 1024); } while (0)
; #define PG8_MMA(ai, bj, At, Bt) do { __builtin_amdgcn_s_setprio(1); _Pragma("unroll") for (int m = 0; m < 4; ++m) _Pragma("unroll") for (int n = 0; n < 2; ++n) _Pragma("unroll") for (int k = 0; k < 2; ++k) \
;         acc[ai][bj][m][n] = __builtin_amdgcn_mfma_f32_16x16x32_bf16(Bt[n][k], At[m][k], acc[ai][bj][m][n], 0, 0, 0); __builtin_amdgcn_s_setprio(0); } while (0)
; #define PG8_WAIT_V(n) asm volatile("s_waitcnt vmcnt(" #n ")" ::: "memory")
; #define PG8_WAIT_L(n) asm volatile("s_waitcnt lgkmcnt(" #n ")" ::: "memory")
; #define PG8_BAR __builtin_amdgcn_s_barrier()
; #define PG8_SCHED __builtin_amdgcn_sched_barrier(0)
; template <class Epi, class Sched>
; __device__ __forceinline__ void gemm_phase(LAS unsigned char* lds, const Sched& S, const Epi& E) {
;     ...
;             PG8_LDB(B0, 0, 0); PG8_SCHED; PG8_LDA(At, 0, 0); PG8_STAGE(PG8_SA(1, 1), a1 + hA, vA0, vA1);
;             PG8_WAIT_L(8); PG8_BAR; PG8_WAIT_L(0); PG8_MMA(0, 0, At, B0); PG8_BAR; PG8_SCHED;
;             PG8_LDB(B1, 0, 1); PG8_STAGE(PG8_SB(0, 0), b2, xB0, xB1);
;             PG8_BAR; PG8_WAIT_L(0); PG8_MMA(0, 1, At, B1); PG8_BAR;
;             PG8_LDA(At, 0, 1); PG8_STAGE(PG8_SA(0, 0), a2, xA0, xA1);
;             PG8_BAR; PG8_WAIT_L(0); PG8_MMA(1, 0, At, B0); PG8_BAR; PG8_SCHED;
;             PG8_STAGE(PG8_SB(0, 1), b2 + xhB, xB0, xB1);
;             PG8_WAIT_V(6); PG8_BAR; PG8_MMA(1, 1, At, B1); PG8_BAR;
;             PG8_LDB(B0, 1, 0); PG8_SCHED; PG8_LDA(At, 1, 0); PG8_STAGE(PG8_SA(0, 1), a2 + xhA, xA0, xA1);
.Lrot_body_3:
	ds_read_b128 v[158:161], v138
	ds_read_b128 v[182:185], v138 offset:1024
	ds_read_b128 v[186:189], v138 offset:2048
	ds_read_b128 v[190:193], v138 offset:3072
	v_lshl_add_u64 v[138:139], s[26:27], 0, v[132:133]
	s_add_i32 m0, s48, 0xc000
	ds_read_b128 v[194:197], v143
	ds_read_b128 v[198:201], v143 offset:1024
	ds_read_b128 v[202:205], v143 offset:2048
	ds_read_b128 v[206:209], v143 offset:3072
	ds_read_b128 v[210:213], v143 offset:4096
	ds_read_b128 v[214:217], v143 offset:5120
	ds_read_b128 v[218:221], v143 offset:6144
	ds_read_b128 v[222:225], v143 offset:7168
	global_load_lds_dwordx4 v[138:139], off
	v_lshl_add_u64 v[138:139], s[26:27], 0, v[134:135]
	s_add_i32 m0, s48, 0xe000
	s_nop 0
	global_load_lds_dwordx4 v[138:139], off
	s_waitcnt lgkmcnt(8)
	s_barrier
	s_waitcnt lgkmcnt(0)
	v_mfma_f32_16x16x32_bf16 v[124:127], v[158:161], v[194:197], v[124:127]
	v_mfma_f32_16x16x32_bf16 v[120:123], v[186:189], v[194:197], v[120:123]
	v_mfma_f32_16x16x32_bf16 v[112:115], v[158:161], v[202:205], v[112:115]
	v_mfma_f32_16x16x32_bf16 v[104:107], v[186:189], v[202:205], v[104:107]
	v_mfma_f32_16x16x32_bf16 v[96:99], v[158:161], v[210:213], v[96:99]
	v_mfma_f32_16x16x32_bf16 v[88:91], v[186:189], v[210:213], v[88:91]
	v_mfma_f32_16x16x32_bf16 v[80:83], v[158:161], v[218:221], v[80:83]
	v_mfma_f32_16x16x32_bf16 v[72:75], v[186:189], v[218:221], v[72:75]
	v_mfma_f32_16x16x32_bf16 v[124:127], v[182:185], v[198:201], v[124:127]
	v_mfma_f32_16x16x32_bf16 v[120:123], v[190:193], v[198:201], v[120:123]
	v_mfma_f32_16x16x32_bf16 v[112:115], v[182:185], v[206:209], v[112:115]
	v_mfma_f32_16x16x32_bf16 v[104:107], v[190:193], v[206:209], v[104:107]
	v_mfma_f32_16x16x32_bf16 v[96:99], v[182:185], v[214:217], v[96:99]
	v_mfma_f32_16x16x32_bf16 v[88:91], v[190:193], v[214:217], v[88:91]
	v_mfma_f32_16x16x32_bf16 v[80:83], v[182:185], v[222:225], v[80:83]
	v_mfma_f32_16x16x32_bf16 v[72:75], v[190:193], v[222:225], v[72:75]
	s_barrier
	s_add_i32 s69, 0, 0x14000
	s_add_i32 s21, s21, s43
	v_add_u32_e32 v138, s69, v155
	s_mov_b32 m0, s21
	ds_read_b128 v[226:229], v138
	ds_read_b128 v[230:233], v138 offset:1024
	ds_read_b128 v[234:237], v138 offset:2048
	ds_read_b128 v[238:241], v138 offset:3072
	global_load_lds_dwordx4 v136, s[38:39]
	s_add_i32 m0, s21, 0x2000
	v_mov_b32_e32 v147, v137
	global_load_lds_dwordx4 v146, s[38:39]
	v_lshl_add_u64 v[138:139], s[38:39], 0, v[136:137]
	v_lshl_add_u64 v[140:141], s[38:39], 0, v[146:147]
	s_mov_b32 m0, s48
	v_lshl_add_u64 v[242:243], s[40:41], 0, v[150:151]
	s_waitcnt lgkmcnt(0)
	s_barrier
	v_mfma_f32_16x16x32_bf16 v[116:119], v[226:229], v[194:197], v[116:119]
	v_mfma_f32_16x16x32_bf16 v[108:111], v[234:237], v[194:197], v[108:111]
	v_mfma_f32_16x16x32_bf16 v[100:103], v[226:229], v[202:205], v[100:103]
	v_mfma_f32_16x16x32_bf16 v[92:95], v[234:237], v[202:205], v[92:95]
	v_mfma_f32_16x16x32_bf16 v[84:87], v[226:229], v[210:213], v[84:87]
	v_mfma_f32_16x16x32_bf16 v[76:79], v[234:237], v[210:213], v[76:79]
	v_mfma_f32_16x16x32_bf16 v[68:71], v[226:229], v[218:221], v[68:71]
	v_mfma_f32_16x16x32_bf16 v[64:67], v[234:237], v[218:221], v[64:67]
	v_mfma_f32_16x16x32_bf16 v[116:119], v[230:233], v[198:201], v[116:119]
	v_mfma_f32_16x16x32_bf16 v[108:111], v[238:241], v[198:201], v[108:111]
	v_mfma_f32_16x16x32_bf16 v[100:103], v[230:233], v[206:209], v[100:103]
	v_mfma_f32_16x16x32_bf16 v[92:95], v[238:241], v[206:209], v[92:95]
	v_mfma_f32_16x16x32_bf16 v[84:87], v[230:233], v[214:217], v[84:87]
	v_mfma_f32_16x16x32_bf16 v[76:79], v[238:241], v[214:217], v[76:79]
	v_mfma_f32_16x16x32_bf16 v[68:71], v[230:233], v[222:225], v[68:71]
	v_mfma_f32_16x16x32_bf16 v[64:67], v[238:241], v[222:225], v[64:67]
	s_barrier
	ds_read_b128 v[194:197], v143 offset:16384
	ds_read_b128 v[198:201], v143 offset:17408
	ds_read_b128 v[202:205], v143 offset:18432
	ds_read_b128 v[206:209], v143 offset:19456
	ds_read_b128 v[210:213], v143 offset:20480
	ds_read_b128 v[214:217], v143 offset:21504
	ds_read_b128 v[218:221], v143 offset:22528
	ds_read_b128 v[222:225], v143 offset:23552
	global_load_lds_dwordx4 v[242:243], off
	v_lshl_add_u64 v[244:245], s[40:41], 0, v[148:149]
	s_mov_b32 m0, s49
	s_nop 0
	global_load_lds_dwordx4 v[244:245], off
	s_barrier
	s_waitcnt lgkmcnt(0)
	v_mfma_f32_16x16x32_bf16 v[60:63], v[158:161], v[194:197], v[60:63]
	v_mfma_f32_16x16x32_bf16 v[56:59], v[186:189], v[194:197], v[56:59]
	v_mfma_f32_16x16x32_bf16 v[44:47], v[158:161], v[202:205], v[44:47]
	v_mfma_f32_16x16x32_bf16 v[40:43], v[186:189], v[202:205], v[40:43]
	v_mfma_f32_16x16x32_bf16 v[28:31], v[158:161], v[210:213], v[28:31]
	v_mfma_f32_16x16x32_bf16 v[24:27], v[186:189], v[210:213], v[24:27]
	v_mfma_f32_16x16x32_bf16 v[12:15], v[158:161], v[218:221], v[12:15]
	v_mfma_f32_16x16x32_bf16 v[8:11], v[186:189], v[218:221], v[8:11]
	v_mfma_f32_16x16x32_bf16 v[60:63], v[182:185], v[198:201], v[60:63]
	v_mfma_f32_16x16x32_bf16 v[56:59], v[190:193], v[198:201], v[56:59]
	v_mfma_f32_16x16x32_bf16 v[44:47], v[182:185], v[206:209], v[44:47]
	v_mfma_f32_16x16x32_bf16 v[40:43], v[190:193], v[206:209], v[40:43]
	v_mfma_f32_16x16x32_bf16 v[28:31], v[182:185], v[214:217], v[28:31]
	v_mfma_f32_16x16x32_bf16 v[24:27], v[190:193], v[214:217], v[24:27]
	v_mfma_f32_16x16x32_bf16 v[12:15], v[182:185], v[222:225], v[12:15]
	v_mfma_f32_16x16x32_bf16 v[8:11], v[190:193], v[222:225], v[8:11]
	s_barrier
	s_add_u32 s70, s38, 0x80000
	s_addc_u32 s71, s39, 0
	s_add_i32 s21, s69, s43
	s_mov_b32 m0, s21
	s_nop 0
	global_load_lds_dwordx4 v136, s[70:71]
	s_add_i32 m0, s21, 0x2000
	s_nop 0
	global_load_lds_dwordx4 v146, s[70:71]
	s_add_i32 s21, 0, 0x18000
	v_add_u32_e32 v147, s21, v155
	s_waitcnt vmcnt(6)
	s_barrier
; #define PG8_STAGE(bufoff, gbase, v0, v1) do { \
;         __builtin_amdgcn_global_load_lds((const unsigned*)((const char*)(gbase) + (v0)), (LAS unsigned*)(lds + (bufoff) + ldsw), 16, 0, 0); \
;         __builtin_amdgcn_global_load_lds((const unsigned*)((const char*)(gbase) + (v1)), (LAS unsigned*)(lds + (bufoff) + ldsw + 8192), 16, 0, 0); } while (0)
; #define PG8_LDA(dst, b, h) do { _Pragma("unroll") for (int m = 0; m < 4; ++m) _Pragma("unroll") for (int k = 0; k < 2; ++k) dst[m][k] = *(const LAS bf16x8*)(lds + PG8_SA(b, h) + aoff + m * 2048 + k * 1024); } while (0)
; #define PG8_LDB(dst, b, h) do { _Pragma("unroll") for (int n = 0; n < 2; ++n) _Pragma("unroll") for (int k = 0; k < 2; ++k) dst[n][k] = *(const LAS bf16x8*)(lds + PG8_SB(b, h) + boff + n * 2048 + k * 1024); } while (0)
; #define PG8_MMA(ai, bj, At, Bt) do { __builtin_amdgcn_s_setprio(1); _Pragma("unroll") for (int m = 0; m < 4; ++m) _Pragma("unroll") for (int n = 0; n < 2; ++n) _Pragma("unroll") for (int k = 0; k < 2; ++k) \
;         acc[ai][bj][m][n] = __builtin_amdgcn_mfma_f32_16x16x32_bf16(Bt[n][k], At[m][k], acc[ai][bj][m][n], 0, 0, 0); __builtin_amdgcn_s_setprio(0); } while (0)
; #define PG8_WAIT_V(n) asm volatile("s_waitcnt vmcnt(" #n ")" ::: "memory")
; #define PG8_WAIT_L(n) asm volatile("s_waitcnt lgkmcnt(" #n ")" ::: "memory")
; #define PG8_BAR __builtin_amdgcn_s_barrier()
; #define PG8_SCHED __builtin_amdgcn_sched_barrier(0)
; template <class Epi, class Sched>
; __device__ __forceinline__ void gemm_phase(LAS unsigned char* lds, const Sched& S, const Epi& E) {
;     ...
;             PG8_WAIT_V(6); PG8_BAR; PG8_MMA(1, 1, At, B1); PG8_BAR;
;             PG8_LDB(B0, 1, 0); PG8_SCHED; PG8_LDA(At, 1, 0); PG8_STAGE(PG8_SA(0, 1), a2 + xhA, xA0, xA1);
;             PG8_WAIT_L(8); PG8_BAR; PG8_WAIT_L(0); PG8_MMA(0, 0, At, B0); PG8_BAR; PG8_SCHED;
;             PG8_LDB(B1, 1, 1); PG8_STAGE(PG8_SB(1, 0), b3, xB0, xB1);
;             PG8_BAR; PG8_WAIT_L(0); PG8_MMA(0, 1, At, B1); PG8_BAR;
	v_mfma_f32_16x16x32_bf16 v[52:55], v[226:229], v[194:197], v[52:55]
	v_mfma_f32_16x16x32_bf16 v[48:51], v[234:237], v[194:197], v[48:51]
	v_mfma_f32_16x16x32_bf16 v[36:39], v[226:229], v[202:205], v[36:39]
	v_mfma_f32_16x16x32_bf16 v[32:35], v[234:237], v[202:205], v[32:35]
	v_mfma_f32_16x16x32_bf16 v[20:23], v[226:229], v[210:213], v[20:23]
	v_mfma_f32_16x16x32_bf16 v[16:19], v[234:237], v[210:213], v[16:19]
	v_mfma_f32_16x16x32_bf16 v[4:7], v[226:229], v[218:221], v[4:7]
	v_mfma_f32_16x16x32_bf16 v[0:3], v[234:237], v[218:221], v[0:3]
	v_mfma_f32_16x16x32_bf16 v[52:55], v[230:233], v[198:201], v[52:55]
	v_mfma_f32_16x16x32_bf16 v[48:51], v[238:241], v[198:201], v[48:51]
	v_mfma_f32_16x16x32_bf16 v[36:39], v[230:233], v[206:209], v[36:39]
	v_mfma_f32_16x16x32_bf16 v[32:35], v[238:241], v[206:209], v[32:35]
	v_mfma_f32_16x16x32_bf16 v[20:23], v[230:233], v[214:217], v[20:23]
	v_mfma_f32_16x16x32_bf16 v[16:19], v[238:241], v[214:217], v[16:19]
	v_mfma_f32_16x16x32_bf16 v[4:7], v[230:233], v[222:225], v[4:7]
	v_mfma_f32_16x16x32_bf16 v[0:3], v[238:241], v[222:225], v[0:3]
	s_barrier
	ds_read_b128 v[158:161], v147
	ds_read_b128 v[182:185], v147 offset:1024
	ds_read_b128 v[186:189], v147 offset:2048
	ds_read_b128 v[190:193], v147 offset:3072
	s_add_u32 s40, s40, 0x80000
	s_addc_u32 s41, s41, 0
	s_mov_b32 m0, s50
	v_lshl_add_u64 v[150:151], s[40:41], 0, v[150:151]
	ds_read_b128 v[194:197], v143 offset:32768
	ds_read_b128 v[198:201], v143 offset:33792
	ds_read_b128 v[202:205], v143 offset:34816
	ds_read_b128 v[206:209], v143 offset:35840
	ds_read_b128 v[210:213], v143 offset:36864
	ds_read_b128 v[214:217], v143 offset:37888
	ds_read_b128 v[218:221], v143 offset:38912
	ds_read_b128 v[222:225], v143 offset:39936
	global_load_lds_dwordx4 v[150:151], off
	v_lshl_add_u64 v[148:149], s[40:41], 0, v[148:149]
	s_mov_b32 m0, s51
	s_nop 0
	global_load_lds_dwordx4 v[148:149], off
	s_waitcnt lgkmcnt(8)
	s_barrier
	s_waitcnt lgkmcnt(0)
	v_mfma_f32_16x16x32_bf16 v[124:127], v[158:161], v[194:197], v[124:127]
	v_mfma_f32_16x16x32_bf16 v[120:123], v[186:189], v[194:197], v[120:123]
	v_mfma_f32_16x16x32_bf16 v[112:115], v[158:161], v[202:205], v[112:115]
	v_mfma_f32_16x16x32_bf16 v[104:107], v[186:189], v[202:205], v[104:107]
	v_mfma_f32_16x16x32_bf16 v[96:99], v[158:161], v[210:213], v[96:99]
	v_mfma_f32_16x16x32_bf16 v[88:91], v[186:189], v[210:213], v[88:91]
	v_mfma_f32_16x16x32_bf16 v[80:83], v[158:161], v[218:221], v[80:83]
	v_mfma_f32_16x16x32_bf16 v[72:75], v[186:189], v[218:221], v[72:75]
	v_mfma_f32_16x16x32_bf16 v[124:127], v[182:185], v[198:201], v[124:127]
	v_mfma_f32_16x16x32_bf16 v[120:123], v[190:193], v[198:201], v[120:123]
	v_mfma_f32_16x16x32_bf16 v[112:115], v[182:185], v[206:209], v[112:115]
	v_mfma_f32_16x16x32_bf16 v[104:107], v[190:193], v[206:209], v[104:107]
	v_mfma_f32_16x16x32_bf16 v[96:99], v[182:185], v[214:217], v[96:99]
	v_mfma_f32_16x16x32_bf16 v[88:91], v[190:193], v[214:217], v[88:91]
	v_mfma_f32_16x16x32_bf16 v[80:83], v[182:185], v[222:225], v[80:83]
	v_mfma_f32_16x16x32_bf16 v[72:75], v[190:193], v[222:225], v[72:75]
	s_barrier
	s_add_i32 s40, 0, 0x1c000
	s_add_i32 s21, s21, s43
	v_add_u32_e32 v147, s40, v155
	v_lshl_add_u64 v[138:139], v[138:139], 0, s[44:45]
	s_mov_b32 m0, s21
	ds_read_b128 v[148:151], v147
	ds_read_b128 v[226:229], v147 offset:1024
	ds_read_b128 v[230:233], v147 offset:2048
	ds_read_b128 v[234:237], v147 offset:3072
	global_load_lds_dwordx4 v[138:139], off
	v_lshl_add_u64 v[138:139], v[140:141], 0, s[44:45]
	s_add_i32 m0, s21, 0x2000
	s_nop 0
	global_load_lds_dwordx4 v[138:139], off
	s_mov_b32 m0, s64
	v_lshl_add_u64 v[138:139], v[242:243], 0, s[44:45]
	s_waitcnt lgkmcnt(0)
	s_barrier
; #define PG8_STAGE(bufoff, gbase, v0, v1) do { \
;         __builtin_amdgcn_global_load_lds((const unsigned*)((const char*)(gbase) + (v0)), (LAS unsigned*)(lds + (bufoff) + ldsw), 16, 0, 0); \
;         __builtin_amdgcn_global_load_lds((const unsigned*)((const char*)(gbase) + (v1)), (LAS unsigned*)(lds + (bufoff) + ldsw + 8192), 16, 0, 0); } while (0)
; #define PG8_LDA(dst, b, h) do { _Pragma("unroll") for (int m = 0; m < 4; ++m) _Pragma("unroll") for (int k = 0; k < 2; ++k) dst[m][k] = *(const LAS bf16x8*)(lds + PG8_SA(b, h) + aoff + m * 2048 + k * 1024); } while (0)
; #define PG8_MMA(ai, bj, At, Bt) do { __builtin_amdgcn_s_setprio(1); _Pragma("unroll") for (int m = 0; m < 4; ++m) _Pragma("unroll") for (int n = 0; n < 2; ++n) _Pragma("unroll") for (int k = 0; k < 2; ++k) \
;         acc[ai][bj][m][n] = __builtin_amdgcn_mfma_f32_16x16x32_bf16(Bt[n][k], At[m][k], acc[ai][bj][m][n], 0, 0, 0); __builtin_amdgcn_s_setprio(0); } while (0)
; #define PG8_WAIT_V(n) asm volatile("s_waitcnt vmcnt(" #n ")" ::: "memory")
; #define PG8_WAIT_L(n) asm volatile("s_waitcnt lgkmcnt(" #n ")" ::: "memory")
; #define PG8_BAR __builtin_amdgcn_s_barrier()
; #define PG8_SCHED __builtin_amdgcn_sched_barrier(0)
; template <class Epi, class Sched>
; __device__ __forceinline__ void gemm_phase(LAS unsigned char* lds, const Sched& S, const Epi& E) {
;     ...
;         for (int t = 0; t < nt; t += 2) {
;             const bool last = (t == nt - 2);
;             const char* a1 = cA + (size_t)(t + 1) * kstep;
;             const char* a2 = last ? nA : cA + (size_t)(t + 2) * kstep; const char* b2 = last ? nB : cB + (size_t)(t + 2) * kstep;
;             const char* a3 = a2 + kstep; const char* b3 = b2 + kstep;
;             const unsigned xA0 = last ? nvA0 : vA0, xA1 = last ? nvA1 : vA1, xB0 = last ? nvB0 : vB0, xB1 = last ? nvB1 : vB1;
;     ...
;             PG8_BAR; PG8_WAIT_L(0); PG8_MMA(0, 1, At, B1); PG8_BAR;
;             PG8_LDA(At, 1, 1); PG8_STAGE(PG8_SA(1, 0), a3, xA0, xA1);
;             PG8_BAR; PG8_WAIT_L(0); PG8_MMA(1, 0, At, B0); PG8_BAR; PG8_SCHED;
;             PG8_STAGE(PG8_SB(1, 1), b3 + xhB, xB0, xB1);
;             PG8_WAIT_V(6); PG8_BAR; PG8_MMA(1, 1, At, B1); PG8_BAR;
	v_mfma_f32_16x16x32_bf16 v[116:119], v[148:151], v[194:197], v[116:119]
	v_mfma_f32_16x16x32_bf16 v[108:111], v[230:233], v[194:197], v[108:111]
	v_mfma_f32_16x16x32_bf16 v[100:103], v[148:151], v[202:205], v[100:103]
	v_mfma_f32_16x16x32_bf16 v[92:95], v[230:233], v[202:205], v[92:95]
	v_mfma_f32_16x16x32_bf16 v[84:87], v[148:151], v[210:213], v[84:87]
	v_mfma_f32_16x16x32_bf16 v[76:79], v[230:233], v[210:213], v[76:79]
	v_mfma_f32_16x16x32_bf16 v[68:71], v[148:151], v[218:221], v[68:71]
	v_mfma_f32_16x16x32_bf16 v[64:67], v[230:233], v[218:221], v[64:67]
	v_mfma_f32_16x16x32_bf16 v[116:119], v[226:229], v[198:201], v[116:119]
	v_mfma_f32_16x16x32_bf16 v[108:111], v[234:237], v[198:201], v[108:111]
	v_mfma_f32_16x16x32_bf16 v[100:103], v[226:229], v[206:209], v[100:103]
	v_mfma_f32_16x16x32_bf16 v[92:95], v[234:237], v[206:209], v[92:95]
	v_mfma_f32_16x16x32_bf16 v[84:87], v[226:229], v[214:217], v[84:87]
	v_mfma_f32_16x16x32_bf16 v[76:79], v[234:237], v[214:217], v[76:79]
	v_mfma_f32_16x16x32_bf16 v[68:71], v[226:229], v[222:225], v[68:71]
	v_mfma_f32_16x16x32_bf16 v[64:67], v[234:237], v[222:225], v[64:67]
	s_barrier
	ds_read_b128 v[194:197], v143 offset:49152
	ds_read_b128 v[198:201], v143 offset:50176
	ds_read_b128 v[202:205], v143 offset:51200
	ds_read_b128 v[206:209], v143 offset:52224
	ds_read_b128 v[210:213], v143 offset:53248
	ds_read_b128 v[214:217], v143 offset:54272
	ds_read_b128 v[218:221], v143 offset:55296
	ds_read_b128 v[222:225], v143 offset:56320
	global_load_lds_dwordx4 v[138:139], off
	v_lshl_add_u64 v[138:139], v[244:245], 0, s[44:45]
	s_mov_b32 m0, s65
	s_nop 0
	global_load_lds_dwordx4 v[138:139], off
	s_barrier
	s_waitcnt lgkmcnt(0)
	v_mfma_f32_16x16x32_bf16 v[60:63], v[158:161], v[194:197], v[60:63]
	v_mfma_f32_16x16x32_bf16 v[56:59], v[186:189], v[194:197], v[56:59]
	v_mfma_f32_16x16x32_bf16 v[44:47], v[158:161], v[202:205], v[44:47]
	v_mfma_f32_16x16x32_bf16 v[40:43], v[186:189], v[202:205], v[40:43]
	v_mfma_f32_16x16x32_bf16 v[28:31], v[158:161], v[210:213], v[28:31]
	v_mfma_f32_16x16x32_bf16 v[24:27], v[186:189], v[210:213], v[24:27]
	v_mfma_f32_16x16x32_bf16 v[12:15], v[158:161], v[218:221], v[12:15]
	v_mfma_f32_16x16x32_bf16 v[8:11], v[186:189], v[218:221], v[8:11]
	v_mfma_f32_16x16x32_bf16 v[60:63], v[182:185], v[198:201], v[60:63]
	v_mfma_f32_16x16x32_bf16 v[56:59], v[190:193], v[198:201], v[56:59]
	v_mfma_f32_16x16x32_bf16 v[44:47], v[182:185], v[206:209], v[44:47]
	v_mfma_f32_16x16x32_bf16 v[40:43], v[190:193], v[206:209], v[40:43]
	v_mfma_f32_16x16x32_bf16 v[28:31], v[182:185], v[214:217], v[28:31]
	v_mfma_f32_16x16x32_bf16 v[24:27], v[190:193], v[214:217], v[24:27]
	v_mfma_f32_16x16x32_bf16 v[12:15], v[182:185], v[222:225], v[12:15]
	v_mfma_f32_16x16x32_bf16 v[8:11], v[190:193], v[222:225], v[8:11]
	s_barrier
	s_add_u32 s38, s38, 0x80080
	s_addc_u32 s39, s39, 0
	s_add_i32 s21, s40, s43
	s_mov_b32 m0, s21
	s_nop 0
	global_load_lds_dwordx4 v136, s[38:39]
	s_add_i32 m0, s21, 0x2000
	s_nop 0
	global_load_lds_dwordx4 v146, s[38:39]
	s_add_i32 s15, s15, 2
	s_add_u32 s26, s26, 0x100
	s_addc_u32 s27, s27, 0
	s_add_u32 s34, s34, 0x100
	s_addc_u32 s35, s35, 0
	s_waitcnt vmcnt(6)
	s_barrier
	v_mfma_f32_16x16x32_bf16 v[52:55], v[148:151], v[194:197], v[52:55]
	v_mfma_f32_16x16x32_bf16 v[48:51], v[230:233], v[194:197], v[48:51]
	v_mfma_f32_16x16x32_bf16 v[36:39], v[148:151], v[202:205], v[36:39]
	v_mfma_f32_16x16x32_bf16 v[32:35], v[230:233], v[202:205], v[32:35]
	v_mfma_f32_16x16x32_bf16 v[20:23], v[148:151], v[210:213], v[20:23]
	v_mfma_f32_16x16x32_bf16 v[16:19], v[230:233], v[210:213], v[16:19]
	v_mfma_f32_16x16x32_bf16 v[4:7], v[148:151], v[218:221], v[4:7]
	v_mfma_f32_16x16x32_bf16 v[0:3], v[230:233], v[218:221], v[0:3]
	v_mfma_f32_16x16x32_bf16 v[52:55], v[226:229], v[198:201], v[52:55]
	v_mfma_f32_16x16x32_bf16 v[48:51], v[234:237], v[198:201], v[48:51]
	v_mfma_f32_16x16x32_bf16 v[36:39], v[226:229], v[206:209], v[36:39]
	v_mfma_f32_16x16x32_bf16 v[32:35], v[234:237], v[206:209], v[32:35]
	v_mfma_f32_16x16x32_bf16 v[20:23], v[226:229], v[214:217], v[20:23]
	v_mfma_f32_16x16x32_bf16 v[16:19], v[234:237], v[214:217], v[16:19]
	v_mfma_f32_16x16x32_bf16 v[4:7], v[226:229], v[222:225], v[4:7]
	v_mfma_f32_16x16x32_bf16 v[0:3], v[234:237], v[222:225], v[0:3]
	s_cmp_gt_u32 s15, 29
	s_cbranch_scc1 .Lrot_exit_3
	s_cmp_eq_u32 s15, 28
	s_cselect_b64 s[40:41], -1, 0
	s_and_b64 vcc, exec, s[40:41]
	v_mov_b64_e32 v[148:149], v[130:131]
	v_mov_b64_e32 v[150:151], v[128:129]
	v_mov_b32_e32 v146, v156
	v_mov_b32_e32 v136, v145
	s_mov_b64 s[38:39], s[24:25]
	s_cbranch_vccnz .Lrot_join_3
	v_mov_b64_e32 v[148:149], v[134:135]
	v_mov_b64_e32 v[150:151], v[132:133]
	v_mov_b32_e32 v146, v142
	v_mov_b32_e32 v136, v144
	s_mov_b64 s[38:39], s[34:35]

; #define PG8_STAGE(bufoff, gbase, v0, v1) do { \
;         __builtin_amdgcn_global_load_lds((const unsigned*)((const char*)(gbase) + (v0)), (LAS unsigned*)(lds + (bufoff) + ldsw), 16, 0, 0); \
;         __builtin_amdgcn_global_load_lds((const unsigned*)((const char*)(gbase) + (v1)), (LAS unsigned*)(lds + (bufoff) + ldsw + 8192), 16, 0, 0); } while (0)
; #define PG8_LDA(dst, b, h) do { _Pragma("unroll") for (int m = 0; m < 4; ++m) _Pragma("unroll") for (int k = 0; k < 2; ++k) dst[m][k] = *(const LAS bf16x8*)(lds + PG8_SA(b, h) + aoff + m * 2048 + k * 1024); } while (0)
; #define PG8_LDB(dst, b, h) do { _Pragma("unroll") for (int n = 0; n < 2; ++n) _Pragma("unroll") for (int k = 0; k < 2; ++k) dst[n][k] = *(const LAS bf16x8*)(lds + PG8_SB(b, h) + boff + n * 2048 + k * 1024); } while (0)
; #define PG8_MMA(ai, bj, At, Bt) do { __builtin_amdgcn_s_setprio(1); _Pragma("unroll") for (int m = 0; m < 4; ++m) _Pragma("unroll") for (int n = 0; n < 2; ++n) _Pragma("unroll") for (int k = 0; k < 2; ++k) \
;         acc[ai][bj][m][n] = __builtin_amdgcn_mfma_f32_16x16x32_bf16(Bt[n][k], At[m][k], acc[ai][bj][m][n], 0, 0, 0); __builtin_amdgcn_s_setprio(0); } while (0)
; #define PG8_WAIT_V(n) asm volatile("s_waitcnt vmcnt(" #n ")" ::: "memory")
; #define PG8_WAIT_L(n) asm volatile("s_waitcnt lgkmcnt(" #n ")" ::: "memory")
; #define PG8_BAR __builtin_amdgcn_s_barrier()
; #define PG8_SCHED __builtin_amdgcn_sched_barrier(0)
; template <class Epi, class Sched>
; __device__ __forceinline__ void gemm_phase(LAS unsigned char* lds, const Sched& S, const Epi& E) {
;     ...
;             PG8_LDB(B0, 0, 0); PG8_SCHED; PG8_LDA(At, 0, 0); PG8_STAGE(PG8_SA(1, 1), a1 + hA, vA0, vA1);
;             PG8_WAIT_L(8); PG8_BAR; PG8_WAIT_L(0); PG8_MMA(0, 0, At, B0); PG8_BAR; PG8_SCHED;
;             PG8_LDB(B1, 0, 1); PG8_STAGE(PG8_SB(0, 0), b2, xB0, xB1);
;             PG8_BAR; PG8_WAIT_L(0); PG8_MMA(0, 1, At, B1); PG8_BAR;
;             PG8_LDA(At, 0, 1); PG8_STAGE(PG8_SA(0, 0), a2, xA0, xA1);
;             PG8_BAR; PG8_WAIT_L(0); PG8_MMA(1, 0, At, B0); PG8_BAR; PG8_SCHED;
;             PG8_STAGE(PG8_SB(0, 1), b2 + xhB, xB0, xB1);
;             PG8_WAIT_V(6); PG8_BAR; PG8_MMA(1, 1, At, B1); PG8_BAR;
;             PG8_LDB(B0, 1, 0); PG8_SCHED; PG8_LDA(At, 1, 0); PG8_STAGE(PG8_SA(0, 1), a2 + xhA, xA0, xA1);
.Lrot_body_4:
	ds_read_b128 v[150:153], v138
	ds_read_b128 v[154:157], v138 offset:1024
	ds_read_b128 v[158:161], v138 offset:2048
	ds_read_b128 v[182:185], v138 offset:3072
	v_lshl_add_u64 v[138:139], s[24:25], 0, v[136:137]
	s_add_i32 m0, s49, 0xc000
	ds_read_b128 v[186:189], v148
	ds_read_b128 v[190:193], v148 offset:1024
	ds_read_b128 v[194:197], v148 offset:2048
	ds_read_b128 v[198:201], v148 offset:3072
	ds_read_b128 v[202:205], v148 offset:4096
	ds_read_b128 v[206:209], v148 offset:5120
	ds_read_b128 v[210:213], v148 offset:6144
	ds_read_b128 v[214:217], v148 offset:7168
	global_load_lds_dwordx4 v[138:139], off
	v_lshl_add_u64 v[138:139], s[24:25], 0, v[132:133]
	s_add_i32 m0, s49, 0xe000
	s_nop 0
	global_load_lds_dwordx4 v[138:139], off
	s_waitcnt lgkmcnt(8)
	s_barrier
	s_waitcnt lgkmcnt(0)
	v_mfma_f32_16x16x32_bf16 v[124:127], v[150:153], v[186:189], v[124:127]
	v_mfma_f32_16x16x32_bf16 v[120:123], v[158:161], v[186:189], v[120:123]
	v_mfma_f32_16x16x32_bf16 v[108:111], v[150:153], v[194:197], v[108:111]
	v_mfma_f32_16x16x32_bf16 v[104:107], v[158:161], v[194:197], v[104:107]
	v_mfma_f32_16x16x32_bf16 v[100:103], v[150:153], v[202:205], v[100:103]
	v_mfma_f32_16x16x32_bf16 v[96:99], v[158:161], v[202:205], v[96:99]
	v_mfma_f32_16x16x32_bf16 v[84:87], v[150:153], v[210:213], v[84:87]
	v_mfma_f32_16x16x32_bf16 v[80:83], v[158:161], v[210:213], v[80:83]
	v_mfma_f32_16x16x32_bf16 v[124:127], v[154:157], v[190:193], v[124:127]
	v_mfma_f32_16x16x32_bf16 v[120:123], v[182:185], v[190:193], v[120:123]
	v_mfma_f32_16x16x32_bf16 v[108:111], v[154:157], v[198:201], v[108:111]
	v_mfma_f32_16x16x32_bf16 v[104:107], v[182:185], v[198:201], v[104:107]
	v_mfma_f32_16x16x32_bf16 v[100:103], v[154:157], v[206:209], v[100:103]
	v_mfma_f32_16x16x32_bf16 v[96:99], v[182:185], v[206:209], v[96:99]
	v_mfma_f32_16x16x32_bf16 v[84:87], v[154:157], v[214:217], v[84:87]
	v_mfma_f32_16x16x32_bf16 v[80:83], v[182:185], v[214:217], v[80:83]
	s_barrier
	s_add_i32 s82, 0, 0x14000
	v_add_u32_e32 v138, s82, v147
	s_add_i32 s15, s15, s48
	ds_read_b128 v[218:221], v138
	ds_read_b128 v[222:225], v138 offset:1024
	ds_read_b128 v[226:229], v138 offset:2048
	ds_read_b128 v[230:233], v138 offset:3072
	v_lshl_add_u64 v[138:139], s[34:35], 0, v[142:143]
	s_mov_b32 m0, s15
	v_lshl_add_u64 v[140:141], s[34:35], 0, v[134:135]
	global_load_lds_dwordx4 v[138:139], off
	s_add_i32 m0, s15, 0x2000
	s_nop 0
	global_load_lds_dwordx4 v[140:141], off
	s_mov_b32 m0, s49
	v_lshl_add_u64 v[234:235], s[38:39], 0, v[142:143]
	s_waitcnt lgkmcnt(0)
	s_barrier
	v_mfma_f32_16x16x32_bf16 v[116:119], v[218:221], v[186:189], v[116:119]
	v_mfma_f32_16x16x32_bf16 v[112:115], v[226:229], v[186:189], v[112:115]
	v_mfma_f32_16x16x32_bf16 v[92:95], v[218:221], v[194:197], v[92:95]
	v_mfma_f32_16x16x32_bf16 v[88:91], v[226:229], v[194:197], v[88:91]
	v_mfma_f32_16x16x32_bf16 v[76:79], v[218:221], v[202:205], v[76:79]
	v_mfma_f32_16x16x32_bf16 v[72:75], v[226:229], v[202:205], v[72:75]
	v_mfma_f32_16x16x32_bf16 v[68:71], v[218:221], v[210:213], v[68:71]
	v_mfma_f32_16x16x32_bf16 v[64:67], v[226:229], v[210:213], v[64:67]
	v_mfma_f32_16x16x32_bf16 v[116:119], v[222:225], v[190:193], v[116:119]
	v_mfma_f32_16x16x32_bf16 v[112:115], v[230:233], v[190:193], v[112:115]
	v_mfma_f32_16x16x32_bf16 v[92:95], v[222:225], v[198:201], v[92:95]
	v_mfma_f32_16x16x32_bf16 v[88:91], v[230:233], v[198:201], v[88:91]
	v_mfma_f32_16x16x32_bf16 v[76:79], v[222:225], v[206:209], v[76:79]
	v_mfma_f32_16x16x32_bf16 v[72:75], v[230:233], v[206:209], v[72:75]
	v_mfma_f32_16x16x32_bf16 v[68:71], v[222:225], v[214:217], v[68:71]
	v_mfma_f32_16x16x32_bf16 v[64:67], v[230:233], v[214:217], v[64:67]
	s_barrier
	ds_read_b128 v[186:189], v148 offset:16384
	ds_read_b128 v[190:193], v148 offset:17408
	ds_read_b128 v[194:197], v148 offset:18432
	ds_read_b128 v[198:201], v148 offset:19456
	ds_read_b128 v[202:205], v148 offset:20480
	ds_read_b128 v[206:209], v148 offset:21504
	ds_read_b128 v[210:213], v148 offset:22528
	ds_read_b128 v[214:217], v148 offset:23552
	global_load_lds_dwordx4 v[234:235], off
	v_lshl_add_u64 v[236:237], s[38:39], 0, v[134:135]
	s_mov_b32 m0, s50
	s_nop 0
	global_load_lds_dwordx4 v[236:237], off
	s_barrier
	s_waitcnt lgkmcnt(0)
	v_mfma_f32_16x16x32_bf16 v[60:63], v[150:153], v[186:189], v[60:63]
	v_mfma_f32_16x16x32_bf16 v[56:59], v[158:161], v[186:189], v[56:59]
	v_mfma_f32_16x16x32_bf16 v[44:47], v[150:153], v[194:197], v[44:47]
	v_mfma_f32_16x16x32_bf16 v[40:43], v[158:161], v[194:197], v[40:43]
	v_mfma_f32_16x16x32_bf16 v[28:31], v[150:153], v[202:205], v[28:31]
	v_mfma_f32_16x16x32_bf16 v[24:27], v[158:161], v[202:205], v[24:27]
	v_mfma_f32_16x16x32_bf16 v[12:15], v[150:153], v[210:213], v[12:15]
	v_mfma_f32_16x16x32_bf16 v[8:11], v[158:161], v[210:213], v[8:11]
	v_mfma_f32_16x16x32_bf16 v[60:63], v[154:157], v[190:193], v[60:63]
	v_mfma_f32_16x16x32_bf16 v[56:59], v[182:185], v[190:193], v[56:59]
	v_mfma_f32_16x16x32_bf16 v[44:47], v[154:157], v[198:201], v[44:47]
	v_mfma_f32_16x16x32_bf16 v[40:43], v[182:185], v[198:201], v[40:43]
	v_mfma_f32_16x16x32_bf16 v[28:31], v[154:157], v[206:209], v[28:31]
	v_mfma_f32_16x16x32_bf16 v[24:27], v[182:185], v[206:209], v[24:27]
	v_mfma_f32_16x16x32_bf16 v[12:15], v[154:157], v[214:217], v[12:15]
	v_mfma_f32_16x16x32_bf16 v[8:11], v[182:185], v[214:217], v[8:11]
	s_barrier
	s_add_u32 s70, s34, 0x200000
	s_addc_u32 s71, s35, 0
	s_add_i32 s15, s82, s48
	v_lshl_add_u64 v[150:151], s[70:71], 0, v[142:143]
	s_mov_b32 m0, s15
	s_nop 0
	global_load_lds_dwordx4 v[150:151], off
	v_lshl_add_u64 v[150:151], s[70:71], 0, v[134:135]
	s_add_i32 m0, s15, 0x2000
	s_nop 0
	global_load_lds_dwordx4 v[150:151], off
	s_add_i32 s15, 0, 0x18000
	v_add_u32_e32 v149, s15, v147
	s_waitcnt vmcnt(6)
	s_barrier
; #define PG8_STAGE(bufoff, gbase, v0, v1) do { \
;         __builtin_amdgcn_global_load_lds((const unsigned*)((const char*)(gbase) + (v0)), (LAS unsigned*)(lds + (bufoff) + ldsw), 16, 0, 0); \
;         __builtin_amdgcn_global_load_lds((const unsigned*)((const char*)(gbase) + (v1)), (LAS unsigned*)(lds + (bufoff) + ldsw + 8192), 16, 0, 0); } while (0)
; #define PG8_LDA(dst, b, h) do { _Pragma("unroll") for (int m = 0; m < 4; ++m) _Pragma("unroll") for (int k = 0; k < 2; ++k) dst[m][k] = *(const LAS bf16x8*)(lds + PG8_SA(b, h) + aoff + m * 2048 + k * 1024); } while (0)
; #define PG8_LDB(dst, b, h) do { _Pragma("unroll") for (int n = 0; n < 2; ++n) _Pragma("unroll") for (int k = 0; k < 2; ++k) dst[n][k] = *(const LAS bf16x8*)(lds + PG8_SB(b, h) + boff + n * 2048 + k * 1024); } while (0)
; #define PG8_MMA(ai, bj, At, Bt) do { __builtin_amdgcn_s_setprio(1); _Pragma("unroll") for (int m = 0; m < 4; ++m) _Pragma("unroll") for (int n = 0; n < 2; ++n) _Pragma("unroll") for (int k = 0; k < 2; ++k) \
;         acc[ai][bj][m][n] = __builtin_amdgcn_mfma_f32_16x16x32_bf16(Bt[n][k], At[m][k], acc[ai][bj][m][n], 0, 0, 0); __builtin_amdgcn_s_setprio(0); } while (0)
; #define PG8_WAIT_V(n) asm volatile("s_waitcnt vmcnt(" #n ")" ::: "memory")
; #define PG8_WAIT_L(n) asm volatile("s_waitcnt lgkmcnt(" #n ")" ::: "memory")
; #define PG8_BAR __builtin_amdgcn_s_barrier()
; #define PG8_SCHED __builtin_amdgcn_sched_barrier(0)
; template <class Epi, class Sched>
; __device__ __forceinline__ void gemm_phase(LAS unsigned char* lds, const Sched& S, const Epi& E) {
;     ...
;             PG8_WAIT_V(6); PG8_BAR; PG8_MMA(1, 1, At, B1); PG8_BAR;
;             PG8_LDB(B0, 1, 0); PG8_SCHED; PG8_LDA(At, 1, 0); PG8_STAGE(PG8_SA(0, 1), a2 + xhA, xA0, xA1);
;             PG8_WAIT_L(8); PG8_BAR; PG8_WAIT_L(0); PG8_MMA(0, 0, At, B0); PG8_BAR; PG8_SCHED;
;             PG8_LDB(B1, 1, 1); PG8_STAGE(PG8_SB(1, 0), b3, xB0, xB1);
;             PG8_BAR; PG8_WAIT_L(0); PG8_MMA(0, 1, At, B1); PG8_BAR;
	v_mfma_f32_16x16x32_bf16 v[52:55], v[218:221], v[186:189], v[52:55]
	v_mfma_f32_16x16x32_bf16 v[48:51], v[226:229], v[186:189], v[48:51]
	v_mfma_f32_16x16x32_bf16 v[36:39], v[218:221], v[194:197], v[36:39]
	v_mfma_f32_16x16x32_bf16 v[32:35], v[226:229], v[194:197], v[32:35]
	v_mfma_f32_16x16x32_bf16 v[20:23], v[218:221], v[202:205], v[20:23]
	v_mfma_f32_16x16x32_bf16 v[16:19], v[226:229], v[202:205], v[16:19]
	v_mfma_f32_16x16x32_bf16 v[4:7], v[218:221], v[210:213], v[4:7]
	v_mfma_f32_16x16x32_bf16 v[0:3], v[226:229], v[210:213], v[0:3]
	v_mfma_f32_16x16x32_bf16 v[52:55], v[222:225], v[190:193], v[52:55]
	v_mfma_f32_16x16x32_bf16 v[48:51], v[230:233], v[190:193], v[48:51]
	v_mfma_f32_16x16x32_bf16 v[36:39], v[222:225], v[198:201], v[36:39]
	v_mfma_f32_16x16x32_bf16 v[32:35], v[230:233], v[198:201], v[32:35]
	v_mfma_f32_16x16x32_bf16 v[20:23], v[222:225], v[206:209], v[20:23]
	v_mfma_f32_16x16x32_bf16 v[16:19], v[230:233], v[206:209], v[16:19]
	v_mfma_f32_16x16x32_bf16 v[4:7], v[222:225], v[214:217], v[4:7]
	v_mfma_f32_16x16x32_bf16 v[0:3], v[230:233], v[214:217], v[0:3]
	s_barrier
	ds_read_b128 v[150:153], v149
	ds_read_b128 v[154:157], v149 offset:1024
	ds_read_b128 v[158:161], v149 offset:2048
	ds_read_b128 v[182:185], v149 offset:3072
	s_add_u32 s38, s38, 0x200000
	s_addc_u32 s39, s39, 0
	s_mov_b32 m0, s51
	v_lshl_add_u64 v[218:219], s[38:39], 0, v[142:143]
	ds_read_b128 v[186:189], v148 offset:32768
	ds_read_b128 v[190:193], v148 offset:33792
	ds_read_b128 v[194:197], v148 offset:34816
	ds_read_b128 v[198:201], v148 offset:35840
	ds_read_b128 v[202:205], v148 offset:36864
	ds_read_b128 v[206:209], v148 offset:37888
	ds_read_b128 v[210:213], v148 offset:38912
	ds_read_b128 v[214:217], v148 offset:39936
	global_load_lds_dwordx4 v[218:219], off
	v_lshl_add_u64 v[218:219], s[38:39], 0, v[134:135]
	s_mov_b32 m0, s54
	s_nop 0
	global_load_lds_dwordx4 v[218:219], off
	s_waitcnt lgkmcnt(8)
	s_barrier
	s_waitcnt lgkmcnt(0)
	v_mfma_f32_16x16x32_bf16 v[124:127], v[150:153], v[186:189], v[124:127]
	v_mfma_f32_16x16x32_bf16 v[120:123], v[158:161], v[186:189], v[120:123]
	v_mfma_f32_16x16x32_bf16 v[108:111], v[150:153], v[194:197], v[108:111]
	v_mfma_f32_16x16x32_bf16 v[104:107], v[158:161], v[194:197], v[104:107]
	v_mfma_f32_16x16x32_bf16 v[100:103], v[150:153], v[202:205], v[100:103]
	v_mfma_f32_16x16x32_bf16 v[96:99], v[158:161], v[202:205], v[96:99]
	v_mfma_f32_16x16x32_bf16 v[84:87], v[150:153], v[210:213], v[84:87]
	v_mfma_f32_16x16x32_bf16 v[80:83], v[158:161], v[210:213], v[80:83]
	v_mfma_f32_16x16x32_bf16 v[124:127], v[154:157], v[190:193], v[124:127]
	v_mfma_f32_16x16x32_bf16 v[120:123], v[182:185], v[190:193], v[120:123]
	v_mfma_f32_16x16x32_bf16 v[108:111], v[154:157], v[198:201], v[108:111]
	v_mfma_f32_16x16x32_bf16 v[104:107], v[182:185], v[198:201], v[104:107]
	v_mfma_f32_16x16x32_bf16 v[100:103], v[154:157], v[206:209], v[100:103]
	v_mfma_f32_16x16x32_bf16 v[96:99], v[182:185], v[206:209], v[96:99]
	v_mfma_f32_16x16x32_bf16 v[84:87], v[154:157], v[214:217], v[84:87]
	v_mfma_f32_16x16x32_bf16 v[80:83], v[182:185], v[214:217], v[80:83]
	s_barrier
	s_add_i32 s38, 0, 0x1c000
	s_add_i32 s15, s15, s48
	v_add_u32_e32 v149, s38, v147
	v_lshl_add_u64 v[138:139], v[138:139], 0, s[44:45]
	s_mov_b32 m0, s15
	ds_read_b128 v[218:221], v149
	ds_read_b128 v[222:225], v149 offset:1024
	ds_read_b128 v[226:229], v149 offset:2048
	ds_read_b128 v[230:233], v149 offset:3072
	global_load_lds_dwordx4 v[138:139], off
	v_lshl_add_u64 v[138:139], v[140:141], 0, s[44:45]
	s_add_i32 m0, s15, 0x2000
	s_nop 0
	global_load_lds_dwordx4 v[138:139], off
	s_mov_b32 m0, s65
	v_lshl_add_u64 v[138:139], v[234:235], 0, s[44:45]
	s_waitcnt lgkmcnt(0)
	s_barrier
; #define PG8_STAGE(bufoff, gbase, v0, v1) do { \
;         __builtin_amdgcn_global_load_lds((const unsigned*)((const char*)(gbase) + (v0)), (LAS unsigned*)(lds + (bufoff) + ldsw), 16, 0, 0); \
;         __builtin_amdgcn_global_load_lds((const unsigned*)((const char*)(gbase) + (v1)), (LAS unsigned*)(lds + (bufoff) + ldsw + 8192), 16, 0, 0); } while (0)
; #define PG8_LDA(dst, b, h) do { _Pragma("unroll") for (int m = 0; m < 4; ++m) _Pragma("unroll") for (int k = 0; k < 2; ++k) dst[m][k] = *(const LAS bf16x8*)(lds + PG8_SA(b, h) + aoff + m * 2048 + k * 1024); } while (0)
; #define PG8_MMA(ai, bj, At, Bt) do { __builtin_amdgcn_s_setprio(1); _Pragma("unroll") for (int m = 0; m < 4; ++m) _Pragma("unroll") for (int n = 0; n < 2; ++n) _Pragma("unroll") for (int k = 0; k < 2; ++k) \
;         acc[ai][bj][m][n] = __builtin_amdgcn_mfma_f32_16x16x32_bf16(Bt[n][k], At[m][k], acc[ai][bj][m][n], 0, 0, 0); __builtin_amdgcn_s_setprio(0); } while (0)
; #define PG8_WAIT_V(n) asm volatile("s_waitcnt vmcnt(" #n ")" ::: "memory")
; #define PG8_WAIT_L(n) asm volatile("s_waitcnt lgkmcnt(" #n ")" ::: "memory")
; #define PG8_BAR __builtin_amdgcn_s_barrier()
; #define PG8_SCHED __builtin_amdgcn_sched_barrier(0)
; template <class Epi, class Sched>
; __device__ __forceinline__ void gemm_phase(LAS unsigned char* lds, const Sched& S, const Epi& E) {
;     ...
;         for (int t = 0; t < nt; t += 2) {
;             const bool last = (t == nt - 2);
;             const char* a1 = cA + (size_t)(t + 1) * kstep;
;             const char* a2 = last ? nA : cA + (size_t)(t + 2) * kstep; const char* b2 = last ? nB : cB + (size_t)(t + 2) * kstep;
;             const char* a3 = a2 + kstep; const char* b3 = b2 + kstep;
;             const unsigned xA0 = last ? nvA0 : vA0, xA1 = last ? nvA1 : vA1, xB0 = last ? nvB0 : vB0, xB1 = last ? nvB1 : vB1;
;     ...
;             PG8_BAR; PG8_WAIT_L(0); PG8_MMA(0, 1, At, B1); PG8_BAR;
;             PG8_LDA(At, 1, 1); PG8_STAGE(PG8_SA(1, 0), a3, xA0, xA1);
;             PG8_BAR; PG8_WAIT_L(0); PG8_MMA(1, 0, At, B0); PG8_BAR; PG8_SCHED;
;             PG8_STAGE(PG8_SB(1, 1), b3 + xhB, xB0, xB1);
;             PG8_WAIT_V(6); PG8_BAR; PG8_MMA(1, 1, At, B1); PG8_BAR;
	v_mfma_f32_16x16x32_bf16 v[116:119], v[218:221], v[186:189], v[116:119]
	v_mfma_f32_16x16x32_bf16 v[112:115], v[226:229], v[186:189], v[112:115]
	v_mfma_f32_16x16x32_bf16 v[92:95], v[218:221], v[194:197], v[92:95]
	v_mfma_f32_16x16x32_bf16 v[88:91], v[226:229], v[194:197], v[88:91]
	v_mfma_f32_16x16x32_bf16 v[76:79], v[218:221], v[202:205], v[76:79]
	v_mfma_f32_16x16x32_bf16 v[72:75], v[226:229], v[202:205], v[72:75]
	v_mfma_f32_16x16x32_bf16 v[68:71], v[218:221], v[210:213], v[68:71]
	v_mfma_f32_16x16x32_bf16 v[64:67], v[226:229], v[210:213], v[64:67]
	v_mfma_f32_16x16x32_bf16 v[116:119], v[222:225], v[190:193], v[116:119]
	v_mfma_f32_16x16x32_bf16 v[112:115], v[230:233], v[190:193], v[112:115]
	v_mfma_f32_16x16x32_bf16 v[92:95], v[222:225], v[198:201], v[92:95]
	v_mfma_f32_16x16x32_bf16 v[88:91], v[230:233], v[198:201], v[88:91]
	v_mfma_f32_16x16x32_bf16 v[76:79], v[222:225], v[206:209], v[76:79]
	v_mfma_f32_16x16x32_bf16 v[72:75], v[230:233], v[206:209], v[72:75]
	v_mfma_f32_16x16x32_bf16 v[68:71], v[222:225], v[214:217], v[68:71]
	v_mfma_f32_16x16x32_bf16 v[64:67], v[230:233], v[214:217], v[64:67]
	s_barrier
	ds_read_b128 v[186:189], v148 offset:49152
	ds_read_b128 v[190:193], v148 offset:50176
	ds_read_b128 v[194:197], v148 offset:51200
	ds_read_b128 v[198:201], v148 offset:52224
	ds_read_b128 v[202:205], v148 offset:53248
	ds_read_b128 v[206:209], v148 offset:54272
	ds_read_b128 v[210:213], v148 offset:55296
	ds_read_b128 v[214:217], v148 offset:56320
	global_load_lds_dwordx4 v[138:139], off
	v_lshl_add_u64 v[138:139], v[236:237], 0, s[44:45]
	s_mov_b32 m0, s66
	s_nop 0
	global_load_lds_dwordx4 v[138:139], off
	s_barrier
	s_waitcnt lgkmcnt(0)
	v_mfma_f32_16x16x32_bf16 v[60:63], v[150:153], v[186:189], v[60:63]
	v_mfma_f32_16x16x32_bf16 v[56:59], v[158:161], v[186:189], v[56:59]
	v_mfma_f32_16x16x32_bf16 v[44:47], v[150:153], v[194:197], v[44:47]
	v_mfma_f32_16x16x32_bf16 v[40:43], v[158:161], v[194:197], v[40:43]
	v_mfma_f32_16x16x32_bf16 v[28:31], v[150:153], v[202:205], v[28:31]
	v_mfma_f32_16x16x32_bf16 v[24:27], v[158:161], v[202:205], v[24:27]
	v_mfma_f32_16x16x32_bf16 v[12:15], v[150:153], v[210:213], v[12:15]
	v_mfma_f32_16x16x32_bf16 v[8:11], v[158:161], v[210:213], v[8:11]
	v_mfma_f32_16x16x32_bf16 v[60:63], v[154:157], v[190:193], v[60:63]
	v_mfma_f32_16x16x32_bf16 v[56:59], v[182:185], v[190:193], v[56:59]
	v_mfma_f32_16x16x32_bf16 v[44:47], v[154:157], v[198:201], v[44:47]
	v_mfma_f32_16x16x32_bf16 v[40:43], v[182:185], v[198:201], v[40:43]
	v_mfma_f32_16x16x32_bf16 v[28:31], v[154:157], v[206:209], v[28:31]
	v_mfma_f32_16x16x32_bf16 v[24:27], v[182:185], v[206:209], v[24:27]
	v_mfma_f32_16x16x32_bf16 v[12:15], v[154:157], v[214:217], v[12:15]
	v_mfma_f32_16x16x32_bf16 v[8:11], v[182:185], v[214:217], v[8:11]
	s_barrier
	s_add_u32 s34, s34, 0x200080
	s_addc_u32 s35, s35, 0
	s_add_i32 s15, s38, s48
	v_lshl_add_u64 v[138:139], s[34:35], 0, v[142:143]
	s_mov_b32 m0, s15
	v_lshl_add_u64 v[134:135], s[34:35], 0, v[134:135]
	global_load_lds_dwordx4 v[138:139], off
	s_add_i32 m0, s15, 0x2000
	s_nop 0
	global_load_lds_dwordx4 v[134:135], off
	s_add_i32 s11, s11, 2
	s_add_u32 s24, s24, 0x100
	s_addc_u32 s25, s25, 0
	s_add_u32 s26, s26, 0x100
	s_addc_u32 s27, s27, 0
	s_waitcnt vmcnt(6)
	s_barrier
	v_mfma_f32_16x16x32_bf16 v[52:55], v[218:221], v[186:189], v[52:55]
	v_mfma_f32_16x16x32_bf16 v[48:51], v[226:229], v[186:189], v[48:51]
	v_mfma_f32_16x16x32_bf16 v[36:39], v[218:221], v[194:197], v[36:39]
	v_mfma_f32_16x16x32_bf16 v[32:35], v[226:229], v[194:197], v[32:35]
	v_mfma_f32_16x16x32_bf16 v[20:23], v[218:221], v[202:205], v[20:23]
	v_mfma_f32_16x16x32_bf16 v[16:19], v[226:229], v[202:205], v[16:19]
	v_mfma_f32_16x16x32_bf16 v[4:7], v[218:221], v[210:213], v[4:7]
	v_mfma_f32_16x16x32_bf16 v[0:3], v[226:229], v[210:213], v[0:3]
	v_mfma_f32_16x16x32_bf16 v[52:55], v[222:225], v[190:193], v[52:55]
	v_mfma_f32_16x16x32_bf16 v[48:51], v[230:233], v[190:193], v[48:51]
	v_mfma_f32_16x16x32_bf16 v[36:39], v[222:225], v[198:201], v[36:39]
	v_mfma_f32_16x16x32_bf16 v[32:35], v[230:233], v[198:201], v[32:35]
	v_mfma_f32_16x16x32_bf16 v[20:23], v[222:225], v[206:209], v[20:23]
	v_mfma_f32_16x16x32_bf16 v[16:19], v[230:233], v[206:209], v[16:19]
	v_mfma_f32_16x16x32_bf16 v[4:7], v[222:225], v[214:217], v[4:7]
	v_mfma_f32_16x16x32_bf16 v[0:3], v[230:233], v[214:217], v[0:3]
	s_cmpk_gt_u32 s11, 0x7d
	s_cbranch_scc1 .Lrot_exit_4
	s_cmpk_eq_i32 s11, 0x7c
	s_cselect_b64 s[38:39], -1, 0
	s_and_b64 vcc, exec, s[38:39]
	v_mov_b64_e32 v[134:135], v[130:131]
	v_mov_b64_e32 v[142:143], v[128:129]
	s_mov_b64 s[34:35], s[22:23]
	s_cbranch_vccnz .Lrot_join_4
	v_mov_b64_e32 v[134:135], v[132:133]
	v_mov_b64_e32 v[142:143], v[136:137]
	s_mov_b64 s[34:35], s[26:27]
